# K-loop: opening barrier 2 MFMAs down and s_setprio 1 raised only after it, so the two early MFMAs fill the hand-off gap at low priority; coalesced epilogue stores
# speedup vs baseline: 1.0022x; 1.0022x over previous
; #define PG8_STAGE(bufoff, gbase, voff) do { _Pragma("unroll") for (int _i = 0; _i < 2; ++_i) \
;         __builtin_amdgcn_global_load_lds((const unsigned*)((const char*)(gbase) + (voff)[_i]), (PG8_LAS unsigned*)(lds + (bufoff) + ldsw + _i * 8192), 16, 0, 0); } while (0)
; #define PG8_LDA(dst, b, h) do { _Pragma("unroll") for (int m = 0; m < 4; ++m) _Pragma("unroll") for (int k = 0; k < 2; ++k) dst[m][k] = *(const PG8_LAS bf16x8*)(lds + PG8_SA(b, h) + aoff + m * 2048 + k * 1024); } while (0)
; #define PG8_LDB(dst, b, h) do { _Pragma("unroll") for (int n = 0; n < 2; ++n) _Pragma("unroll") for (int k = 0; k < 2; ++k) dst[n][k] = *(const PG8_LAS bf16x8*)(lds + PG8_SB(b, h) + boff + n * 2048 + k * 1024); } while (0)
; #define PG8_MMA(ai, bj, At, Bt) do { __builtin_amdgcn_s_setprio(1); _Pragma("unroll") for (int m = 0; m < 4; ++m) _Pragma("unroll") for (int n = 0; n < 2; ++n) _Pragma("unroll") for (int k = 0; k < 2; ++k) \
;         acc[ai][bj][m][n] = __builtin_amdgcn_mfma_f32_16x16x32_bf16(Bt[n][k], At[m][k], acc[ai][bj][m][n], 0, 0, 0); __builtin_amdgcn_s_setprio(0); } while (0)
; #define PG8_WAIT_V(n) asm volatile("s_waitcnt vmcnt(" #n ")" ::: "memory")
; #define PG8_WAIT_L(n) asm volatile("s_waitcnt lgkmcnt(" #n ")" ::: "memory")
; #define PG8_BAR __builtin_amdgcn_s_barrier()
; #define PG8_SCHED __builtin_amdgcn_sched_barrier(0)
; template <class Epi, class Sched, bool ALIGN_EPI = false, bool SP2 = false>
; __device__ __forceinline__ void gemm_phase(PG8_LAS unsigned char* lds, const Gemm g, const Sched& S, const Epi& E, const int wid_in) {
;     ...
;             if constexpr (SP2) {
;             PG8_LDB(B0, 0, 0); PG8_LDB(B1, 0, 1); PG8_SCHED; PG8_LDA(At, 0, 0); PG8_STAGE(PG8_SA(1, 1), a1 + hstepA, voffA);
;             PG8_WAIT_V(8); PG8_WAIT_L(0); PG8_BAR; PG8_MMA(0, 0, At, B0); PG8_MMA(0, 1, At, B1); PG8_BAR; PG8_SCHED;
;             PG8_LDA(At, 0, 1); PG8_STAGE(PG8_SB(0, 0), b2, voffB); PG8_STAGE(PG8_SB(0, 1), b2 + hstep, voffB); PG8_STAGE(PG8_SA(0, 0), a2, voffA);
;             PG8_WAIT_V(8); PG8_WAIT_L(0); PG8_BAR; PG8_MMA(1, 0, At, B0); PG8_MMA(1, 1, At, B1); PG8_BAR; PG8_SCHED;
.LBB0_119:
	s_add_u32 s2, s4, 0xfff80080
	s_addc_u32 s3, s5, -1
	s_add_i32 s47, 0, 0x10000
	s_cmp_eq_u32 s46, 28
	s_cselect_b32 s23, s17, s3
	s_cselect_b32 s22, s42, s2
	s_cselect_b32 s3, s15, s45
	s_cselect_b32 s2, s43, s44
	s_add_i32 s50, 0, 0x14000
	v_add_u32_e32 v142, s47, v202
	s_waitcnt lgkmcnt(0)
	v_add_u32_e32 v184, s50, v202
	ds_read_b128 v[130:133], v142
	ds_read_b128 v[134:137], v142 offset:1024
	ds_read_b128 v[138:141], v142 offset:2048
	ds_read_b128 v[142:145], v142 offset:3072
	ds_read_b128 v[146:149], v184
	ds_read_b128 v[150:153], v184 offset:1024
	ds_read_b128 v[180:183], v184 offset:2048
	ds_read_b128 v[184:187], v184 offset:3072
	v_lshl_add_u64 v[234:235], s[4:5], 0, v[176:177]
	s_add_i32 m0, s34, 0xc000
	ds_read_b128 v[188:191], v205
	ds_read_b128 v[206:209], v205 offset:1024
	ds_read_b128 v[210:213], v205 offset:2048
	ds_read_b128 v[214:217], v205 offset:3072
	ds_read_b128 v[218:221], v205 offset:4096
	ds_read_b128 v[222:225], v205 offset:5120
	ds_read_b128 v[226:229], v205 offset:6144
	ds_read_b128 v[230:233], v205 offset:7168
	global_load_lds_dwordx4 v[234:235], off
	v_lshl_add_u64 v[234:235], s[4:5], 0, v[178:179]
	s_add_i32 m0, s34, 0xe000
	s_nop 0
	global_load_lds_dwordx4 v[234:235], off
	s_waitcnt vmcnt(8)
	s_waitcnt lgkmcnt(0)
	s_waitcnt lgkmcnt(0)
	v_mfma_f32_16x16x32_bf16 v[126:129], v[130:133], v[188:191], v[126:129]
	v_mfma_f32_16x16x32_bf16 v[122:125], v[138:141], v[188:191], v[122:125]
	s_barrier
	s_setprio 1
	v_mfma_f32_16x16x32_bf16 v[110:113], v[130:133], v[210:213], v[110:113]
	v_mfma_f32_16x16x32_bf16 v[106:109], v[138:141], v[210:213], v[106:109]
	v_mfma_f32_16x16x32_bf16 v[94:97], v[130:133], v[218:221], v[94:97]
	v_mfma_f32_16x16x32_bf16 v[90:93], v[138:141], v[218:221], v[90:93]
	v_mfma_f32_16x16x32_bf16 v[78:81], v[130:133], v[226:229], v[78:81]
	v_mfma_f32_16x16x32_bf16 v[74:77], v[138:141], v[226:229], v[74:77]
	v_mfma_f32_16x16x32_bf16 v[126:129], v[134:137], v[206:209], v[126:129]
	v_mfma_f32_16x16x32_bf16 v[122:125], v[142:145], v[206:209], v[122:125]
	v_mfma_f32_16x16x32_bf16 v[110:113], v[134:137], v[214:217], v[110:113]
	v_mfma_f32_16x16x32_bf16 v[106:109], v[142:145], v[214:217], v[106:109]
	v_mfma_f32_16x16x32_bf16 v[94:97], v[134:137], v[222:225], v[94:97]
	v_mfma_f32_16x16x32_bf16 v[90:93], v[142:145], v[222:225], v[90:93]
	v_mfma_f32_16x16x32_bf16 v[78:81], v[134:137], v[230:233], v[78:81]
	v_mfma_f32_16x16x32_bf16 v[74:77], v[142:145], v[230:233], v[74:77]
	s_setprio 0
	s_setprio 1
	v_mfma_f32_16x16x32_bf16 v[118:121], v[146:149], v[188:191], v[118:121]
	v_mfma_f32_16x16x32_bf16 v[114:117], v[180:183], v[188:191], v[114:117]
	v_mfma_f32_16x16x32_bf16 v[102:105], v[146:149], v[210:213], v[102:105]
	v_mfma_f32_16x16x32_bf16 v[98:101], v[180:183], v[210:213], v[98:101]
	v_mfma_f32_16x16x32_bf16 v[86:89], v[146:149], v[218:221], v[86:89]
	v_mfma_f32_16x16x32_bf16 v[82:85], v[180:183], v[218:221], v[82:85]
	v_mfma_f32_16x16x32_bf16 v[70:73], v[146:149], v[226:229], v[70:73]
	v_mfma_f32_16x16x32_bf16 v[66:69], v[180:183], v[226:229], v[66:69]
	v_mfma_f32_16x16x32_bf16 v[118:121], v[150:153], v[206:209], v[118:121]
	v_mfma_f32_16x16x32_bf16 v[114:117], v[184:187], v[206:209], v[114:117]
	v_mfma_f32_16x16x32_bf16 v[102:105], v[150:153], v[214:217], v[102:105]
	v_mfma_f32_16x16x32_bf16 v[98:101], v[184:187], v[214:217], v[98:101]
	v_mfma_f32_16x16x32_bf16 v[86:89], v[150:153], v[222:225], v[86:89]
	v_mfma_f32_16x16x32_bf16 v[82:85], v[184:187], v[222:225], v[82:85]
	v_mfma_f32_16x16x32_bf16 v[70:73], v[150:153], v[230:233], v[70:73]
	v_mfma_f32_16x16x32_bf16 v[66:69], v[184:187], v[230:233], v[66:69]
	s_setprio 0
	s_barrier
	s_add_i32 s47, s47, s27
	v_lshl_add_u64 v[234:235], s[2:3], 0, v[170:171]
	s_mov_b32 m0, s47
	ds_read_b128 v[188:191], v205 offset:16384
	ds_read_b128 v[206:209], v205 offset:17408
	ds_read_b128 v[210:213], v205 offset:18432
	ds_read_b128 v[214:217], v205 offset:19456
	ds_read_b128 v[218:221], v205 offset:20480
	ds_read_b128 v[222:225], v205 offset:21504
	ds_read_b128 v[226:229], v205 offset:22528
	ds_read_b128 v[230:233], v205 offset:23552
	global_load_lds_dwordx4 v[234:235], off
	s_add_i32 m0, s47, 0x2000
	s_add_u32 s48, s2, 0x80000
	v_lshl_add_u64 v[236:237], s[2:3], 0, v[166:167]
	s_addc_u32 s49, s3, 0
	s_add_i32 s47, s50, s27
	global_load_lds_dwordx4 v[236:237], off
	v_lshl_add_u64 v[238:239], s[48:49], 0, v[170:171]
	s_mov_b32 m0, s47
	v_lshl_add_u64 v[240:241], s[22:23], 0, v[168:169]
	global_load_lds_dwordx4 v[238:239], off
	v_lshl_add_u64 v[238:239], s[48:49], 0, v[166:167]
	s_add_i32 m0, s47, 0x2000
	s_nop 0
	global_load_lds_dwordx4 v[238:239], off
	v_lshl_add_u64 v[238:239], s[22:23], 0, v[172:173]
	s_mov_b32 m0, s34
	s_nop 0
	global_load_lds_dwordx4 v[238:239], off
	s_mov_b32 m0, s35
	s_nop 0
	global_load_lds_dwordx4 v[240:241], off
	s_waitcnt vmcnt(8)
	s_waitcnt lgkmcnt(0)
	s_waitcnt lgkmcnt(0)
	v_mfma_f32_16x16x32_bf16 v[62:65], v[130:133], v[188:191], v[62:65]
	v_mfma_f32_16x16x32_bf16 v[58:61], v[138:141], v[188:191], v[58:61]
	s_barrier
; #define PG8_STAGE(bufoff, gbase, voff) do { _Pragma("unroll") for (int _i = 0; _i < 2; ++_i) \
;         __builtin_amdgcn_global_load_lds((const unsigned*)((const char*)(gbase) + (voff)[_i]), (PG8_LAS unsigned*)(lds + (bufoff) + ldsw + _i * 8192), 16, 0, 0); } while (0)
; #define PG8_LDA(dst, b, h) do { _Pragma("unroll") for (int m = 0; m < 4; ++m) _Pragma("unroll") for (int k = 0; k < 2; ++k) dst[m][k] = *(const PG8_LAS bf16x8*)(lds + PG8_SA(b, h) + aoff + m * 2048 + k * 1024); } while (0)
; #define PG8_LDB(dst, b, h) do { _Pragma("unroll") for (int n = 0; n < 2; ++n) _Pragma("unroll") for (int k = 0; k < 2; ++k) dst[n][k] = *(const PG8_LAS bf16x8*)(lds + PG8_SB(b, h) + boff + n * 2048 + k * 1024); } while (0)
; #define PG8_MMA(ai, bj, At, Bt) do { __builtin_amdgcn_s_setprio(1); _Pragma("unroll") for (int m = 0; m < 4; ++m) _Pragma("unroll") for (int n = 0; n < 2; ++n) _Pragma("unroll") for (int k = 0; k < 2; ++k) \
;         acc[ai][bj][m][n] = __builtin_amdgcn_mfma_f32_16x16x32_bf16(Bt[n][k], At[m][k], acc[ai][bj][m][n], 0, 0, 0); __builtin_amdgcn_s_setprio(0); } while (0)
; #define PG8_WAIT_V(n) asm volatile("s_waitcnt vmcnt(" #n ")" ::: "memory")
; #define PG8_WAIT_L(n) asm volatile("s_waitcnt lgkmcnt(" #n ")" ::: "memory")
; #define PG8_BAR __builtin_amdgcn_s_barrier()
; #define PG8_SCHED __builtin_amdgcn_sched_barrier(0)
; template <class Epi, class Sched, bool ALIGN_EPI = false, bool SP2 = false>
; __device__ __forceinline__ void gemm_phase(PG8_LAS unsigned char* lds, const Gemm g, const Sched& S, const Epi& E, const int wid_in) {
;     ...
;             PG8_WAIT_V(8); PG8_WAIT_L(0); PG8_BAR; PG8_MMA(1, 0, At, B0); PG8_MMA(1, 1, At, B1); PG8_BAR; PG8_SCHED;
;             PG8_LDB(B0, 1, 0); PG8_LDB(B1, 1, 1); PG8_SCHED; PG8_LDA(At, 1, 0); PG8_STAGE(PG8_SA(0, 1), a2 + hstepA, voffA);
;             PG8_WAIT_V(8); PG8_WAIT_L(0); PG8_BAR; PG8_MMA(0, 0, At, B0); PG8_MMA(0, 1, At, B1); PG8_BAR; PG8_SCHED;
	s_setprio 1
	v_mfma_f32_16x16x32_bf16 v[46:49], v[130:133], v[210:213], v[46:49]
	v_mfma_f32_16x16x32_bf16 v[42:45], v[138:141], v[210:213], v[42:45]
	v_mfma_f32_16x16x32_bf16 v[30:33], v[130:133], v[218:221], v[30:33]
	v_mfma_f32_16x16x32_bf16 v[26:29], v[138:141], v[218:221], v[26:29]
	v_mfma_f32_16x16x32_bf16 v[14:17], v[130:133], v[226:229], v[14:17]
	v_mfma_f32_16x16x32_bf16 v[10:13], v[138:141], v[226:229], v[10:13]
	v_mfma_f32_16x16x32_bf16 v[62:65], v[134:137], v[206:209], v[62:65]
	v_mfma_f32_16x16x32_bf16 v[58:61], v[142:145], v[206:209], v[58:61]
	v_mfma_f32_16x16x32_bf16 v[46:49], v[134:137], v[214:217], v[46:49]
	v_mfma_f32_16x16x32_bf16 v[42:45], v[142:145], v[214:217], v[42:45]
	v_mfma_f32_16x16x32_bf16 v[30:33], v[134:137], v[222:225], v[30:33]
	v_mfma_f32_16x16x32_bf16 v[26:29], v[142:145], v[222:225], v[26:29]
	v_mfma_f32_16x16x32_bf16 v[14:17], v[134:137], v[230:233], v[14:17]
	v_mfma_f32_16x16x32_bf16 v[10:13], v[142:145], v[230:233], v[10:13]
	s_setprio 0
	s_setprio 1
	v_mfma_f32_16x16x32_bf16 v[54:57], v[146:149], v[188:191], v[54:57]
	v_mfma_f32_16x16x32_bf16 v[50:53], v[180:183], v[188:191], v[50:53]
	v_mfma_f32_16x16x32_bf16 v[38:41], v[146:149], v[210:213], v[38:41]
	v_mfma_f32_16x16x32_bf16 v[34:37], v[180:183], v[210:213], v[34:37]
	v_mfma_f32_16x16x32_bf16 v[22:25], v[146:149], v[218:221], v[22:25]
	v_mfma_f32_16x16x32_bf16 v[18:21], v[180:183], v[218:221], v[18:21]
	v_mfma_f32_16x16x32_bf16 v[6:9], v[146:149], v[226:229], v[6:9]
	v_mfma_f32_16x16x32_bf16 v[2:5], v[180:183], v[226:229], v[2:5]
	v_mfma_f32_16x16x32_bf16 v[54:57], v[150:153], v[206:209], v[54:57]
	v_mfma_f32_16x16x32_bf16 v[50:53], v[184:187], v[206:209], v[50:53]
	v_mfma_f32_16x16x32_bf16 v[38:41], v[150:153], v[214:217], v[38:41]
	v_mfma_f32_16x16x32_bf16 v[34:37], v[184:187], v[214:217], v[34:37]
	v_mfma_f32_16x16x32_bf16 v[22:25], v[150:153], v[222:225], v[22:25]
	v_mfma_f32_16x16x32_bf16 v[18:21], v[184:187], v[222:225], v[18:21]
	v_mfma_f32_16x16x32_bf16 v[6:9], v[150:153], v[230:233], v[6:9]
	v_mfma_f32_16x16x32_bf16 v[2:5], v[184:187], v[230:233], v[2:5]
	s_setprio 0
	s_barrier
	s_add_i32 s47, 0, 0x18000
	s_add_i32 s48, 0, 0x1c000
	v_add_u32_e32 v142, s47, v202
	v_add_u32_e32 v184, s48, v202
	ds_read_b128 v[130:133], v142
	ds_read_b128 v[134:137], v142 offset:1024
	ds_read_b128 v[138:141], v142 offset:2048
	ds_read_b128 v[142:145], v142 offset:3072
	ds_read_b128 v[146:149], v184
	ds_read_b128 v[150:153], v184 offset:1024
	ds_read_b128 v[180:183], v184 offset:2048
	ds_read_b128 v[184:187], v184 offset:3072
	s_add_u32 s22, s22, 0x80000
	s_addc_u32 s23, s23, 0
	s_mov_b32 m0, s36
	v_lshl_add_u64 v[242:243], s[22:23], 0, v[172:173]
	ds_read_b128 v[188:191], v205 offset:32768
	ds_read_b128 v[206:209], v205 offset:33792
	ds_read_b128 v[210:213], v205 offset:34816
	ds_read_b128 v[214:217], v205 offset:35840
	ds_read_b128 v[218:221], v205 offset:36864
	ds_read_b128 v[222:225], v205 offset:37888
	ds_read_b128 v[226:229], v205 offset:38912
	ds_read_b128 v[230:233], v205 offset:39936
	global_load_lds_dwordx4 v[242:243], off
	v_lshl_add_u64 v[242:243], s[22:23], 0, v[168:169]
	s_mov_b32 m0, s37
	s_nop 0
	global_load_lds_dwordx4 v[242:243], off
	s_waitcnt vmcnt(8)
	s_waitcnt lgkmcnt(0)
	s_waitcnt lgkmcnt(0)
	v_mfma_f32_16x16x32_bf16 v[126:129], v[130:133], v[188:191], v[126:129]
	v_mfma_f32_16x16x32_bf16 v[122:125], v[138:141], v[188:191], v[122:125]
	s_barrier
	s_setprio 1
	v_mfma_f32_16x16x32_bf16 v[110:113], v[130:133], v[210:213], v[110:113]
	v_mfma_f32_16x16x32_bf16 v[106:109], v[138:141], v[210:213], v[106:109]
	v_mfma_f32_16x16x32_bf16 v[94:97], v[130:133], v[218:221], v[94:97]
	v_mfma_f32_16x16x32_bf16 v[90:93], v[138:141], v[218:221], v[90:93]
	v_mfma_f32_16x16x32_bf16 v[78:81], v[130:133], v[226:229], v[78:81]
	v_mfma_f32_16x16x32_bf16 v[74:77], v[138:141], v[226:229], v[74:77]
	v_mfma_f32_16x16x32_bf16 v[126:129], v[134:137], v[206:209], v[126:129]
	v_mfma_f32_16x16x32_bf16 v[122:125], v[142:145], v[206:209], v[122:125]
	v_mfma_f32_16x16x32_bf16 v[110:113], v[134:137], v[214:217], v[110:113]
	v_mfma_f32_16x16x32_bf16 v[106:109], v[142:145], v[214:217], v[106:109]
	v_mfma_f32_16x16x32_bf16 v[94:97], v[134:137], v[222:225], v[94:97]
	v_mfma_f32_16x16x32_bf16 v[90:93], v[142:145], v[222:225], v[90:93]
	v_mfma_f32_16x16x32_bf16 v[78:81], v[134:137], v[230:233], v[78:81]
	v_mfma_f32_16x16x32_bf16 v[74:77], v[142:145], v[230:233], v[74:77]
	s_setprio 0
	s_setprio 1
	v_mfma_f32_16x16x32_bf16 v[118:121], v[146:149], v[188:191], v[118:121]
	v_mfma_f32_16x16x32_bf16 v[114:117], v[180:183], v[188:191], v[114:117]
	v_mfma_f32_16x16x32_bf16 v[102:105], v[146:149], v[210:213], v[102:105]
	v_mfma_f32_16x16x32_bf16 v[98:101], v[180:183], v[210:213], v[98:101]
	v_mfma_f32_16x16x32_bf16 v[86:89], v[146:149], v[218:221], v[86:89]
	v_mfma_f32_16x16x32_bf16 v[82:85], v[180:183], v[218:221], v[82:85]
	v_mfma_f32_16x16x32_bf16 v[70:73], v[146:149], v[226:229], v[70:73]
	v_mfma_f32_16x16x32_bf16 v[66:69], v[180:183], v[226:229], v[66:69]
	v_mfma_f32_16x16x32_bf16 v[118:121], v[150:153], v[206:209], v[118:121]
	v_mfma_f32_16x16x32_bf16 v[114:117], v[184:187], v[206:209], v[114:117]
	v_mfma_f32_16x16x32_bf16 v[102:105], v[150:153], v[214:217], v[102:105]
	v_mfma_f32_16x16x32_bf16 v[98:101], v[184:187], v[214:217], v[98:101]
	v_mfma_f32_16x16x32_bf16 v[86:89], v[150:153], v[222:225], v[86:89]
	v_mfma_f32_16x16x32_bf16 v[82:85], v[184:187], v[222:225], v[82:85]
	v_mfma_f32_16x16x32_bf16 v[70:73], v[150:153], v[230:233], v[70:73]
	v_mfma_f32_16x16x32_bf16 v[66:69], v[184:187], v[230:233], v[66:69]
	s_setprio 0
	s_barrier
; #define PG8_STAGE(bufoff, gbase, voff) do { _Pragma("unroll") for (int _i = 0; _i < 2; ++_i) \
;         __builtin_amdgcn_global_load_lds((const unsigned*)((const char*)(gbase) + (voff)[_i]), (PG8_LAS unsigned*)(lds + (bufoff) + ldsw + _i * 8192), 16, 0, 0); } while (0)
; #define PG8_LDA(dst, b, h) do { _Pragma("unroll") for (int m = 0; m < 4; ++m) _Pragma("unroll") for (int k = 0; k < 2; ++k) dst[m][k] = *(const PG8_LAS bf16x8*)(lds + PG8_SA(b, h) + aoff + m * 2048 + k * 1024); } while (0)
; #define PG8_MMA(ai, bj, At, Bt) do { __builtin_amdgcn_s_setprio(1); _Pragma("unroll") for (int m = 0; m < 4; ++m) _Pragma("unroll") for (int n = 0; n < 2; ++n) _Pragma("unroll") for (int k = 0; k < 2; ++k) \
;         acc[ai][bj][m][n] = __builtin_amdgcn_mfma_f32_16x16x32_bf16(Bt[n][k], At[m][k], acc[ai][bj][m][n], 0, 0, 0); __builtin_amdgcn_s_setprio(0); } while (0)
; #define PG8_WAIT_V(n) asm volatile("s_waitcnt vmcnt(" #n ")" ::: "memory")
; #define PG8_WAIT_L(n) asm volatile("s_waitcnt lgkmcnt(" #n ")" ::: "memory")
; #define PG8_BAR __builtin_amdgcn_s_barrier()
; #define PG8_SCHED __builtin_amdgcn_sched_barrier(0)
; template <class Epi, class Sched, bool ALIGN_EPI = false, bool SP2 = false>
; __device__ __forceinline__ void gemm_phase(PG8_LAS unsigned char* lds, const Gemm g, const Sched& S, const Epi& E, const int wid_in) {
;     ...
;         for (int t = 0; t < nt; t += 2) {
;             const bool last = (t == nt - 2);
;             const char* a1 = cA + (size_t)(t + 1) * kstep;
;             const char* a2 = last ? nA : cA + (size_t)(t + 2) * kstep; const char* b2 = last ? nB : cB + (size_t)(t + 2) * kstep;
;             const char* a3 = a2 + kstep; const char* b3 = b2 + kstep;
;     ...
;             PG8_LDA(At, 1, 1); PG8_STAGE(PG8_SB(1, 0), b3, voffB); PG8_STAGE(PG8_SB(1, 1), b3 + hstep, voffB); PG8_STAGE(PG8_SA(1, 0), a3, voffA);
;             PG8_WAIT_V(8); PG8_WAIT_L(0); PG8_BAR; PG8_MMA(1, 0, At, B0); PG8_MMA(1, 1, At, B1); PG8_BAR; PG8_SCHED;
	s_add_i32 s22, s47, s27
	v_lshl_add_u64 v[234:235], v[234:235], 0, s[98:99]
	s_mov_b32 m0, s22
	ds_read_b128 v[188:191], v205 offset:49152
	ds_read_b128 v[206:209], v205 offset:50176
	ds_read_b128 v[210:213], v205 offset:51200
	ds_read_b128 v[214:217], v205 offset:52224
	ds_read_b128 v[218:221], v205 offset:53248
	ds_read_b128 v[222:225], v205 offset:54272
	ds_read_b128 v[226:229], v205 offset:55296
	ds_read_b128 v[230:233], v205 offset:56320
	global_load_lds_dwordx4 v[234:235], off
	s_add_i32 m0, s22, 0x2000
	s_add_u32 s2, s2, 0x80080
	v_lshl_add_u64 v[234:235], v[236:237], 0, s[98:99]
	s_addc_u32 s3, s3, 0
	s_add_i32 s22, s48, s27
	global_load_lds_dwordx4 v[234:235], off
	v_lshl_add_u64 v[234:235], s[2:3], 0, v[170:171]
	s_mov_b32 m0, s22
	s_nop 0
	global_load_lds_dwordx4 v[234:235], off
	v_lshl_add_u64 v[234:235], s[2:3], 0, v[166:167]
	s_add_i32 m0, s22, 0x2000
	s_nop 0
	global_load_lds_dwordx4 v[234:235], off
	v_lshl_add_u64 v[234:235], v[238:239], 0, s[98:99]
	s_mov_b32 m0, s38
	s_nop 0
	global_load_lds_dwordx4 v[234:235], off
	v_lshl_add_u64 v[234:235], v[240:241], 0, s[98:99]
	s_mov_b32 m0, s39
	s_nop 0
	global_load_lds_dwordx4 v[234:235], off
	s_waitcnt vmcnt(8)
	s_waitcnt lgkmcnt(0)
	s_waitcnt lgkmcnt(0)
	v_mfma_f32_16x16x32_bf16 v[62:65], v[130:133], v[188:191], v[62:65]
	v_mfma_f32_16x16x32_bf16 v[58:61], v[138:141], v[188:191], v[58:61]
	s_barrier
	s_setprio 1
	v_mfma_f32_16x16x32_bf16 v[46:49], v[130:133], v[210:213], v[46:49]
	v_mfma_f32_16x16x32_bf16 v[42:45], v[138:141], v[210:213], v[42:45]
	v_mfma_f32_16x16x32_bf16 v[30:33], v[130:133], v[218:221], v[30:33]
	v_mfma_f32_16x16x32_bf16 v[26:29], v[138:141], v[218:221], v[26:29]
	v_mfma_f32_16x16x32_bf16 v[14:17], v[130:133], v[226:229], v[14:17]
	v_mfma_f32_16x16x32_bf16 v[10:13], v[138:141], v[226:229], v[10:13]
	v_mfma_f32_16x16x32_bf16 v[62:65], v[134:137], v[206:209], v[62:65]
	v_mfma_f32_16x16x32_bf16 v[58:61], v[142:145], v[206:209], v[58:61]
	v_mfma_f32_16x16x32_bf16 v[46:49], v[134:137], v[214:217], v[46:49]
	v_mfma_f32_16x16x32_bf16 v[42:45], v[142:145], v[214:217], v[42:45]
	v_mfma_f32_16x16x32_bf16 v[30:33], v[134:137], v[222:225], v[30:33]
	v_mfma_f32_16x16x32_bf16 v[26:29], v[142:145], v[222:225], v[26:29]
	v_mfma_f32_16x16x32_bf16 v[14:17], v[134:137], v[230:233], v[14:17]
	v_mfma_f32_16x16x32_bf16 v[10:13], v[142:145], v[230:233], v[10:13]
	s_setprio 0
	s_setprio 1
	v_mfma_f32_16x16x32_bf16 v[54:57], v[146:149], v[188:191], v[54:57]
	v_mfma_f32_16x16x32_bf16 v[50:53], v[180:183], v[188:191], v[50:53]
	v_mfma_f32_16x16x32_bf16 v[38:41], v[146:149], v[210:213], v[38:41]
	v_mfma_f32_16x16x32_bf16 v[34:37], v[180:183], v[210:213], v[34:37]
	v_mfma_f32_16x16x32_bf16 v[22:25], v[146:149], v[218:221], v[22:25]
	v_mfma_f32_16x16x32_bf16 v[18:21], v[180:183], v[218:221], v[18:21]
	v_mfma_f32_16x16x32_bf16 v[6:9], v[146:149], v[226:229], v[6:9]
	v_mfma_f32_16x16x32_bf16 v[2:5], v[180:183], v[226:229], v[2:5]
	v_mfma_f32_16x16x32_bf16 v[54:57], v[150:153], v[206:209], v[54:57]
	v_mfma_f32_16x16x32_bf16 v[50:53], v[184:187], v[206:209], v[50:53]
	v_mfma_f32_16x16x32_bf16 v[38:41], v[150:153], v[214:217], v[38:41]
	v_mfma_f32_16x16x32_bf16 v[34:37], v[184:187], v[214:217], v[34:37]
	v_mfma_f32_16x16x32_bf16 v[22:25], v[150:153], v[222:225], v[22:25]
	v_mfma_f32_16x16x32_bf16 v[18:21], v[184:187], v[222:225], v[18:21]
	v_mfma_f32_16x16x32_bf16 v[6:9], v[150:153], v[230:233], v[6:9]
	v_mfma_f32_16x16x32_bf16 v[2:5], v[184:187], v[230:233], v[2:5]
	s_setprio 0
	s_barrier
	s_add_i32 s46, s46, 2
	s_add_u32 s4, s4, 0x100
	s_addc_u32 s5, s5, 0
	s_add_u32 s44, s44, 0x100
	s_addc_u32 s45, s45, 0
	s_cmp_gt_u32 s46, 29
	s_cbranch_scc0 .LBB0_119
	s_and_b64 vcc, exec, s[12:13]
	s_cbranch_vccz .LBB0_122
	s_barrier

; #define PG8_STAGE(bufoff, gbase, voff) do { _Pragma("unroll") for (int _i = 0; _i < 2; ++_i) \
;         __builtin_amdgcn_global_load_lds((const unsigned*)((const char*)(gbase) + (voff)[_i]), (PG8_LAS unsigned*)(lds + (bufoff) + ldsw + _i * 8192), 16, 0, 0); } while (0)
; #define PG8_LDA(dst, b, h) do { _Pragma("unroll") for (int m = 0; m < 4; ++m) _Pragma("unroll") for (int k = 0; k < 2; ++k) dst[m][k] = *(const PG8_LAS bf16x8*)(lds + PG8_SA(b, h) + aoff + m * 2048 + k * 1024); } while (0)
; #define PG8_LDB(dst, b, h) do { _Pragma("unroll") for (int n = 0; n < 2; ++n) _Pragma("unroll") for (int k = 0; k < 2; ++k) dst[n][k] = *(const PG8_LAS bf16x8*)(lds + PG8_SB(b, h) + boff + n * 2048 + k * 1024); } while (0)
; #define PG8_MMA(ai, bj, At, Bt) do { __builtin_amdgcn_s_setprio(1); _Pragma("unroll") for (int m = 0; m < 4; ++m) _Pragma("unroll") for (int n = 0; n < 2; ++n) _Pragma("unroll") for (int k = 0; k < 2; ++k) \
;         acc[ai][bj][m][n] = __builtin_amdgcn_mfma_f32_16x16x32_bf16(Bt[n][k], At[m][k], acc[ai][bj][m][n], 0, 0, 0); __builtin_amdgcn_s_setprio(0); } while (0)
; #define PG8_WAIT_V(n) asm volatile("s_waitcnt vmcnt(" #n ")" ::: "memory")
; #define PG8_WAIT_L(n) asm volatile("s_waitcnt lgkmcnt(" #n ")" ::: "memory")
; template <class Epi, class Sched, bool ALIGN_EPI = false, bool SP2 = false>
; __device__ __forceinline__ void gemm_phase(PG8_LAS unsigned char* lds, const Gemm g, const Sched& S, const Epi& E, const int wid_in) {
;     ...
;             const bool last = (t == nt - 2);
;             const char* a1 = cA + (size_t)(t + 1) * kstep;
;             const char* a2 = last ? nA : cA + (size_t)(t + 2) * kstep; const char* b2 = last ? nB : cB + (size_t)(t + 2) * kstep;
;             const char* a3 = a2 + kstep; const char* b3 = b2 + kstep;
;             if (last && has_next) S.a_ready(nxt);
;             if constexpr (SP2) {
;             PG8_LDB(B0, 0, 0); PG8_LDB(B1, 0, 1); PG8_SCHED; PG8_LDA(At, 0, 0); PG8_STAGE(PG8_SA(1, 1), a1 + hstepA, voffA);
;             PG8_WAIT_V(8); PG8_WAIT_L(0); PG8_BAR; PG8_MMA(0, 0, At, B0); PG8_MMA(0, 1, At, B1); PG8_BAR; PG8_SCHED;
;             PG8_LDA(At, 0, 1); PG8_STAGE(PG8_SB(0, 0), b2, voffB); PG8_STAGE(PG8_SB(0, 1), b2 + hstep, voffB); PG8_STAGE(PG8_SA(0, 0), a2, voffA);
;             PG8_WAIT_V(8); PG8_WAIT_L(0); PG8_BAR; PG8_MMA(1, 0, At, B0); PG8_MMA(1, 1, At, B1); PG8_BAR; PG8_SCHED;
.LBB0_375:
	s_add_u32 s0, s26, 0x100
	s_addc_u32 s1, s27, 0
	s_add_i32 s51, 0, 0x10000
	s_cmp_eq_u32 s50, 28
	s_cselect_b32 s11, s23, s1
	s_cselect_b32 s10, s22, s0
	v_add_u32_e32 v145, s51, v147
	s_cselect_b32 s3, s21, s29
	s_cselect_b32 s2, s49, s28
	s_add_i32 s52, 0, 0x14000
	ds_read_b128 v[166:169], v145
	ds_read_b128 v[174:177], v145 offset:1024
	ds_read_b128 v[178:181], v145 offset:2048
	ds_read_b128 v[182:185], v145 offset:3072
	v_add_u32_e32 v145, s52, v147
	ds_read_b128 v[186:189], v145
	ds_read_b128 v[202:205], v145 offset:1024
	ds_read_b128 v[206:209], v145 offset:2048
	ds_read_b128 v[210:213], v145 offset:3072
	v_lshl_add_u64 v[152:153], s[26:27], 0, v[140:141]
	s_add_i32 m0, s38, 0xc000
	ds_read_b128 v[214:217], v150
	ds_read_b128 v[218:221], v150 offset:1024
	ds_read_b128 v[222:225], v150 offset:2048
	ds_read_b128 v[226:229], v150 offset:3072
	ds_read_b128 v[230:233], v150 offset:4096
	ds_read_b128 v[234:237], v150 offset:5120
	ds_read_b128 v[238:241], v150 offset:6144
	ds_read_b128 v[242:245], v150 offset:7168
	global_load_lds_dwordx4 v[152:153], off
	v_lshl_add_u64 v[152:153], s[26:27], 0, v[142:143]
	s_add_i32 m0, s38, 0xe000
	s_nop 0
	global_load_lds_dwordx4 v[152:153], off
	s_waitcnt vmcnt(8)
	s_waitcnt lgkmcnt(0)
	s_waitcnt lgkmcnt(0)
	v_mfma_f32_16x16x32_bf16 v[118:121], v[166:169], v[214:217], v[118:121]
	v_mfma_f32_16x16x32_bf16 v[114:117], v[178:181], v[214:217], v[114:117]
	s_barrier
	s_setprio 1
	v_mfma_f32_16x16x32_bf16 v[98:101], v[166:169], v[222:225], v[98:101]
	v_mfma_f32_16x16x32_bf16 v[106:109], v[178:181], v[222:225], v[106:109]
	v_mfma_f32_16x16x32_bf16 v[82:85], v[166:169], v[230:233], v[82:85]
	v_mfma_f32_16x16x32_bf16 v[90:93], v[178:181], v[230:233], v[90:93]
	v_mfma_f32_16x16x32_bf16 v[74:77], v[166:169], v[238:241], v[74:77]
	v_mfma_f32_16x16x32_bf16 v[66:69], v[178:181], v[238:241], v[66:69]
	v_mfma_f32_16x16x32_bf16 v[118:121], v[174:177], v[218:221], v[118:121]
	v_mfma_f32_16x16x32_bf16 v[114:117], v[182:185], v[218:221], v[114:117]
	v_mfma_f32_16x16x32_bf16 v[98:101], v[174:177], v[226:229], v[98:101]
	v_mfma_f32_16x16x32_bf16 v[106:109], v[182:185], v[226:229], v[106:109]
	v_mfma_f32_16x16x32_bf16 v[82:85], v[174:177], v[234:237], v[82:85]
	v_mfma_f32_16x16x32_bf16 v[90:93], v[182:185], v[234:237], v[90:93]
	v_mfma_f32_16x16x32_bf16 v[74:77], v[174:177], v[242:245], v[74:77]
	v_mfma_f32_16x16x32_bf16 v[66:69], v[182:185], v[242:245], v[66:69]
	s_setprio 0
	s_setprio 1
	v_mfma_f32_16x16x32_bf16 v[122:125], v[186:189], v[214:217], v[122:125]
	v_mfma_f32_16x16x32_bf16 v[126:129], v[206:209], v[214:217], v[126:129]
	v_mfma_f32_16x16x32_bf16 v[102:105], v[186:189], v[222:225], v[102:105]
	v_mfma_f32_16x16x32_bf16 v[110:113], v[206:209], v[222:225], v[110:113]
	v_mfma_f32_16x16x32_bf16 v[86:89], v[186:189], v[230:233], v[86:89]
	v_mfma_f32_16x16x32_bf16 v[94:97], v[206:209], v[230:233], v[94:97]
	v_mfma_f32_16x16x32_bf16 v[70:73], v[186:189], v[238:241], v[70:73]
	v_mfma_f32_16x16x32_bf16 v[78:81], v[206:209], v[238:241], v[78:81]
	v_mfma_f32_16x16x32_bf16 v[122:125], v[202:205], v[218:221], v[122:125]
	v_mfma_f32_16x16x32_bf16 v[126:129], v[210:213], v[218:221], v[126:129]
	v_mfma_f32_16x16x32_bf16 v[102:105], v[202:205], v[226:229], v[102:105]
	v_mfma_f32_16x16x32_bf16 v[110:113], v[210:213], v[226:229], v[110:113]
	v_mfma_f32_16x16x32_bf16 v[86:89], v[202:205], v[234:237], v[86:89]
	v_mfma_f32_16x16x32_bf16 v[94:97], v[210:213], v[234:237], v[94:97]
	v_mfma_f32_16x16x32_bf16 v[70:73], v[202:205], v[242:245], v[70:73]
	v_mfma_f32_16x16x32_bf16 v[78:81], v[210:213], v[242:245], v[78:81]
	s_setprio 0
	s_barrier
	s_add_i32 s26, s51, s37
	v_lshl_add_u64 v[152:153], s[2:3], 0, v[134:135]
	s_mov_b32 m0, s26
	ds_read_b128 v[214:217], v150 offset:16384
	ds_read_b128 v[218:221], v150 offset:17408
	ds_read_b128 v[222:225], v150 offset:18432
	ds_read_b128 v[226:229], v150 offset:19456
	ds_read_b128 v[230:233], v150 offset:20480
	ds_read_b128 v[234:237], v150 offset:21504
	ds_read_b128 v[238:241], v150 offset:22528
	ds_read_b128 v[242:245], v150 offset:23552
	global_load_lds_dwordx4 v[152:153], off
	s_add_i32 m0, s26, 0x2000
	s_add_u32 s26, s2, 0x80000
	v_lshl_add_u64 v[170:171], s[2:3], 0, v[130:131]
	s_addc_u32 s27, s3, 0
	s_add_i32 s51, s52, s37
	global_load_lds_dwordx4 v[170:171], off
	v_lshl_add_u64 v[190:191], s[26:27], 0, v[134:135]
	s_mov_b32 m0, s51
	v_lshl_add_u64 v[246:247], s[10:11], 0, v[132:133]
	global_load_lds_dwordx4 v[190:191], off
	v_lshl_add_u64 v[190:191], s[26:27], 0, v[130:131]
	s_add_i32 m0, s51, 0x2000
	s_nop 0
	global_load_lds_dwordx4 v[190:191], off
	v_lshl_add_u64 v[190:191], s[10:11], 0, v[136:137]
	s_mov_b32 m0, s38
	s_nop 0
	global_load_lds_dwordx4 v[190:191], off
	s_mov_b32 m0, s39
	s_nop 0
	global_load_lds_dwordx4 v[246:247], off
	s_waitcnt vmcnt(8)
	s_waitcnt lgkmcnt(0)
	s_waitcnt lgkmcnt(0)
	v_mfma_f32_16x16x32_bf16 v[34:37], v[166:169], v[214:217], v[34:37]
	v_mfma_f32_16x16x32_bf16 v[46:49], v[178:181], v[214:217], v[46:49]
	s_barrier
; #define PG8_STAGE(bufoff, gbase, voff) do { _Pragma("unroll") for (int _i = 0; _i < 2; ++_i) \
;         __builtin_amdgcn_global_load_lds((const unsigned*)((const char*)(gbase) + (voff)[_i]), (PG8_LAS unsigned*)(lds + (bufoff) + ldsw + _i * 8192), 16, 0, 0); } while (0)
; #define PG8_LDA(dst, b, h) do { _Pragma("unroll") for (int m = 0; m < 4; ++m) _Pragma("unroll") for (int k = 0; k < 2; ++k) dst[m][k] = *(const PG8_LAS bf16x8*)(lds + PG8_SA(b, h) + aoff + m * 2048 + k * 1024); } while (0)
; #define PG8_LDB(dst, b, h) do { _Pragma("unroll") for (int n = 0; n < 2; ++n) _Pragma("unroll") for (int k = 0; k < 2; ++k) dst[n][k] = *(const PG8_LAS bf16x8*)(lds + PG8_SB(b, h) + boff + n * 2048 + k * 1024); } while (0)
; #define PG8_MMA(ai, bj, At, Bt) do { __builtin_amdgcn_s_setprio(1); _Pragma("unroll") for (int m = 0; m < 4; ++m) _Pragma("unroll") for (int n = 0; n < 2; ++n) _Pragma("unroll") for (int k = 0; k < 2; ++k) \
;         acc[ai][bj][m][n] = __builtin_amdgcn_mfma_f32_16x16x32_bf16(Bt[n][k], At[m][k], acc[ai][bj][m][n], 0, 0, 0); __builtin_amdgcn_s_setprio(0); } while (0)
; #define PG8_WAIT_V(n) asm volatile("s_waitcnt vmcnt(" #n ")" ::: "memory")
; #define PG8_WAIT_L(n) asm volatile("s_waitcnt lgkmcnt(" #n ")" ::: "memory")
; #define PG8_BAR __builtin_amdgcn_s_barrier()
; #define PG8_SCHED __builtin_amdgcn_sched_barrier(0)
; template <class Epi, class Sched, bool ALIGN_EPI = false, bool SP2 = false>
; __device__ __forceinline__ void gemm_phase(PG8_LAS unsigned char* lds, const Gemm g, const Sched& S, const Epi& E, const int wid_in) {
;     ...
;             PG8_WAIT_V(8); PG8_WAIT_L(0); PG8_BAR; PG8_MMA(1, 0, At, B0); PG8_MMA(1, 1, At, B1); PG8_BAR; PG8_SCHED;
;             PG8_LDB(B0, 1, 0); PG8_LDB(B1, 1, 1); PG8_SCHED; PG8_LDA(At, 1, 0); PG8_STAGE(PG8_SA(0, 1), a2 + hstepA, voffA);
;             PG8_WAIT_V(8); PG8_WAIT_L(0); PG8_BAR; PG8_MMA(0, 0, At, B0); PG8_MMA(0, 1, At, B1); PG8_BAR; PG8_SCHED;
;             PG8_LDA(At, 1, 1); PG8_STAGE(PG8_SB(1, 0), b3, voffB); PG8_STAGE(PG8_SB(1, 1), b3 + hstep, voffB); PG8_STAGE(PG8_SA(1, 0), a3, voffA);
;             PG8_WAIT_V(8); PG8_WAIT_L(0); PG8_BAR; PG8_MMA(1, 0, At, B0); PG8_MMA(1, 1, At, B1); PG8_BAR; PG8_SCHED;
	s_setprio 1
	v_mfma_f32_16x16x32_bf16 v[10:13], v[166:169], v[222:225], v[10:13]
	v_mfma_f32_16x16x32_bf16 v[6:9], v[178:181], v[222:225], v[6:9]
	v_mfma_f32_16x16x32_bf16 v[42:45], v[166:169], v[230:233], v[42:45]
	v_mfma_f32_16x16x32_bf16 v[58:61], v[178:181], v[230:233], v[58:61]
	v_mfma_f32_16x16x32_bf16 v[22:25], v[166:169], v[238:241], v[22:25]
	v_mfma_f32_16x16x32_bf16 v[2:5], v[178:181], v[238:241], v[2:5]
	v_mfma_f32_16x16x32_bf16 v[34:37], v[174:177], v[218:221], v[34:37]
	v_mfma_f32_16x16x32_bf16 v[46:49], v[182:185], v[218:221], v[46:49]
	v_mfma_f32_16x16x32_bf16 v[10:13], v[174:177], v[226:229], v[10:13]
	v_mfma_f32_16x16x32_bf16 v[6:9], v[182:185], v[226:229], v[6:9]
	v_mfma_f32_16x16x32_bf16 v[42:45], v[174:177], v[234:237], v[42:45]
	v_mfma_f32_16x16x32_bf16 v[58:61], v[182:185], v[234:237], v[58:61]
	v_mfma_f32_16x16x32_bf16 v[22:25], v[174:177], v[242:245], v[22:25]
	v_mfma_f32_16x16x32_bf16 v[2:5], v[182:185], v[242:245], v[2:5]
	s_setprio 0
	s_setprio 1
	v_mfma_f32_16x16x32_bf16 v[38:41], v[186:189], v[214:217], v[38:41]
	v_mfma_f32_16x16x32_bf16 v[54:57], v[206:209], v[214:217], v[54:57]
	v_mfma_f32_16x16x32_bf16 v[14:17], v[186:189], v[222:225], v[14:17]
	v_mfma_f32_16x16x32_bf16 v[26:29], v[206:209], v[222:225], v[26:29]
	v_mfma_f32_16x16x32_bf16 v[50:53], v[186:189], v[230:233], v[50:53]
	v_mfma_f32_16x16x32_bf16 v[62:65], v[206:209], v[230:233], v[62:65]
	v_mfma_f32_16x16x32_bf16 v[18:21], v[186:189], v[238:241], v[18:21]
	v_mfma_f32_16x16x32_bf16 v[30:33], v[206:209], v[238:241], v[30:33]
	v_mfma_f32_16x16x32_bf16 v[38:41], v[202:205], v[218:221], v[38:41]
	v_mfma_f32_16x16x32_bf16 v[54:57], v[210:213], v[218:221], v[54:57]
	v_mfma_f32_16x16x32_bf16 v[14:17], v[202:205], v[226:229], v[14:17]
	v_mfma_f32_16x16x32_bf16 v[26:29], v[210:213], v[226:229], v[26:29]
	v_mfma_f32_16x16x32_bf16 v[50:53], v[202:205], v[234:237], v[50:53]
	v_mfma_f32_16x16x32_bf16 v[62:65], v[210:213], v[234:237], v[62:65]
	v_mfma_f32_16x16x32_bf16 v[18:21], v[202:205], v[242:245], v[18:21]
	v_mfma_f32_16x16x32_bf16 v[30:33], v[210:213], v[242:245], v[30:33]
	s_setprio 0
	s_barrier
	s_add_i32 s26, 0, 0x18000
	v_add_u32_e32 v145, s26, v147
	s_add_i32 s27, 0, 0x1c000
	ds_read_b128 v[166:169], v145
	ds_read_b128 v[174:177], v145 offset:1024
	ds_read_b128 v[178:181], v145 offset:2048
	ds_read_b128 v[182:185], v145 offset:3072
	v_add_u32_e32 v145, s27, v147
	ds_read_b128 v[186:189], v145
	ds_read_b128 v[202:205], v145 offset:1024
	ds_read_b128 v[206:209], v145 offset:2048
	ds_read_b128 v[210:213], v145 offset:3072
	s_add_u32 s10, s10, 0x140000
	s_addc_u32 s11, s11, 0
	s_mov_b32 m0, s40
	v_lshl_add_u64 v[248:249], s[10:11], 0, v[136:137]
	ds_read_b128 v[214:217], v150 offset:32768
	ds_read_b128 v[218:221], v150 offset:33792
	ds_read_b128 v[222:225], v150 offset:34816
	ds_read_b128 v[226:229], v150 offset:35840
	ds_read_b128 v[230:233], v150 offset:36864
	ds_read_b128 v[234:237], v150 offset:37888
	ds_read_b128 v[238:241], v150 offset:38912
	ds_read_b128 v[242:245], v150 offset:39936
	global_load_lds_dwordx4 v[248:249], off
	v_lshl_add_u64 v[248:249], s[10:11], 0, v[132:133]
	s_mov_b32 m0, s41
	s_nop 0
	global_load_lds_dwordx4 v[248:249], off
	s_waitcnt vmcnt(8)
	s_waitcnt lgkmcnt(0)
	s_waitcnt lgkmcnt(0)
	v_mfma_f32_16x16x32_bf16 v[118:121], v[166:169], v[214:217], v[118:121]
	v_mfma_f32_16x16x32_bf16 v[114:117], v[178:181], v[214:217], v[114:117]
	s_barrier
	s_setprio 1
	v_mfma_f32_16x16x32_bf16 v[98:101], v[166:169], v[222:225], v[98:101]
	v_mfma_f32_16x16x32_bf16 v[106:109], v[178:181], v[222:225], v[106:109]
	v_mfma_f32_16x16x32_bf16 v[82:85], v[166:169], v[230:233], v[82:85]
	v_mfma_f32_16x16x32_bf16 v[90:93], v[178:181], v[230:233], v[90:93]
	v_mfma_f32_16x16x32_bf16 v[74:77], v[166:169], v[238:241], v[74:77]
	v_mfma_f32_16x16x32_bf16 v[66:69], v[178:181], v[238:241], v[66:69]
	v_mfma_f32_16x16x32_bf16 v[118:121], v[174:177], v[218:221], v[118:121]
	v_mfma_f32_16x16x32_bf16 v[114:117], v[182:185], v[218:221], v[114:117]
	v_mfma_f32_16x16x32_bf16 v[98:101], v[174:177], v[226:229], v[98:101]
	v_mfma_f32_16x16x32_bf16 v[106:109], v[182:185], v[226:229], v[106:109]
	v_mfma_f32_16x16x32_bf16 v[82:85], v[174:177], v[234:237], v[82:85]
	v_mfma_f32_16x16x32_bf16 v[90:93], v[182:185], v[234:237], v[90:93]
	v_mfma_f32_16x16x32_bf16 v[74:77], v[174:177], v[242:245], v[74:77]
	v_mfma_f32_16x16x32_bf16 v[66:69], v[182:185], v[242:245], v[66:69]
	s_setprio 0
	s_setprio 1
	v_mfma_f32_16x16x32_bf16 v[122:125], v[186:189], v[214:217], v[122:125]
	v_mfma_f32_16x16x32_bf16 v[126:129], v[206:209], v[214:217], v[126:129]
	v_mfma_f32_16x16x32_bf16 v[102:105], v[186:189], v[222:225], v[102:105]
	v_mfma_f32_16x16x32_bf16 v[110:113], v[206:209], v[222:225], v[110:113]
	v_mfma_f32_16x16x32_bf16 v[86:89], v[186:189], v[230:233], v[86:89]
	v_mfma_f32_16x16x32_bf16 v[94:97], v[206:209], v[230:233], v[94:97]
	v_mfma_f32_16x16x32_bf16 v[70:73], v[186:189], v[238:241], v[70:73]
	v_mfma_f32_16x16x32_bf16 v[78:81], v[206:209], v[238:241], v[78:81]
	v_mfma_f32_16x16x32_bf16 v[122:125], v[202:205], v[218:221], v[122:125]
	v_mfma_f32_16x16x32_bf16 v[126:129], v[210:213], v[218:221], v[126:129]
	v_mfma_f32_16x16x32_bf16 v[102:105], v[202:205], v[226:229], v[102:105]
	v_mfma_f32_16x16x32_bf16 v[110:113], v[210:213], v[226:229], v[110:113]
	v_mfma_f32_16x16x32_bf16 v[86:89], v[202:205], v[234:237], v[86:89]
	v_mfma_f32_16x16x32_bf16 v[94:97], v[210:213], v[234:237], v[94:97]
	v_mfma_f32_16x16x32_bf16 v[70:73], v[202:205], v[242:245], v[70:73]
	v_mfma_f32_16x16x32_bf16 v[78:81], v[210:213], v[242:245], v[78:81]
	s_setprio 0
	s_barrier
; #define PG8_STAGE(bufoff, gbase, voff) do { _Pragma("unroll") for (int _i = 0; _i < 2; ++_i) \
;         __builtin_amdgcn_global_load_lds((const unsigned*)((const char*)(gbase) + (voff)[_i]), (PG8_LAS unsigned*)(lds + (bufoff) + ldsw + _i * 8192), 16, 0, 0); } while (0)
; #define PG8_LDA(dst, b, h) do { _Pragma("unroll") for (int m = 0; m < 4; ++m) _Pragma("unroll") for (int k = 0; k < 2; ++k) dst[m][k] = *(const PG8_LAS bf16x8*)(lds + PG8_SA(b, h) + aoff + m * 2048 + k * 1024); } while (0)
; #define PG8_MMA(ai, bj, At, Bt) do { __builtin_amdgcn_s_setprio(1); _Pragma("unroll") for (int m = 0; m < 4; ++m) _Pragma("unroll") for (int n = 0; n < 2; ++n) _Pragma("unroll") for (int k = 0; k < 2; ++k) \
;         acc[ai][bj][m][n] = __builtin_amdgcn_mfma_f32_16x16x32_bf16(Bt[n][k], At[m][k], acc[ai][bj][m][n], 0, 0, 0); __builtin_amdgcn_s_setprio(0); } while (0)
; #define PG8_WAIT_V(n) asm volatile("s_waitcnt vmcnt(" #n ")" ::: "memory")
; #define PG8_WAIT_L(n) asm volatile("s_waitcnt lgkmcnt(" #n ")" ::: "memory")
; #define PG8_BAR __builtin_amdgcn_s_barrier()
; #define PG8_SCHED __builtin_amdgcn_sched_barrier(0)
; template <class Epi, class Sched, bool ALIGN_EPI = false, bool SP2 = false>
; __device__ __forceinline__ void gemm_phase(PG8_LAS unsigned char* lds, const Gemm g, const Sched& S, const Epi& E, const int wid_in) {
;     ...
;         for (int t = 0; t < nt; t += 2) {
;             const bool last = (t == nt - 2);
;             const char* a1 = cA + (size_t)(t + 1) * kstep;
;             const char* a2 = last ? nA : cA + (size_t)(t + 2) * kstep; const char* b2 = last ? nB : cB + (size_t)(t + 2) * kstep;
;             const char* a3 = a2 + kstep; const char* b3 = b2 + kstep;
;     ...
;             PG8_LDA(At, 1, 1); PG8_STAGE(PG8_SB(1, 0), b3, voffB); PG8_STAGE(PG8_SB(1, 1), b3 + hstep, voffB); PG8_STAGE(PG8_SA(1, 0), a3, voffA);
;             PG8_WAIT_V(8); PG8_WAIT_L(0); PG8_BAR; PG8_MMA(1, 0, At, B0); PG8_MMA(1, 1, At, B1); PG8_BAR; PG8_SCHED;
	s_add_i32 s10, s26, s37
	v_lshl_add_u64 v[152:153], v[152:153], 0, s[98:99]
	s_mov_b32 m0, s10
	ds_read_b128 v[214:217], v150 offset:49152
	ds_read_b128 v[218:221], v150 offset:50176
	ds_read_b128 v[222:225], v150 offset:51200
	ds_read_b128 v[226:229], v150 offset:52224
	ds_read_b128 v[230:233], v150 offset:53248
	ds_read_b128 v[234:237], v150 offset:54272
	ds_read_b128 v[238:241], v150 offset:55296
	ds_read_b128 v[242:245], v150 offset:56320
	global_load_lds_dwordx4 v[152:153], off
	s_add_i32 m0, s10, 0x2000
	s_add_u32 s2, s2, 0x80080
	v_lshl_add_u64 v[152:153], v[170:171], 0, s[98:99]
	s_addc_u32 s3, s3, 0
	s_add_i32 s10, s27, s37
	global_load_lds_dwordx4 v[152:153], off
	v_lshl_add_u64 v[152:153], s[2:3], 0, v[134:135]
	s_mov_b32 m0, s10
	s_nop 0
	global_load_lds_dwordx4 v[152:153], off
	v_lshl_add_u64 v[152:153], s[2:3], 0, v[130:131]
	s_add_i32 m0, s10, 0x2000
	s_nop 0
	global_load_lds_dwordx4 v[152:153], off
	v_lshl_add_u64 v[152:153], v[190:191], 0, s[98:99]
	s_mov_b32 m0, s44
	s_nop 0
	global_load_lds_dwordx4 v[152:153], off
	v_lshl_add_u64 v[152:153], v[246:247], 0, s[98:99]
	s_mov_b32 m0, s45
	s_nop 0
	global_load_lds_dwordx4 v[152:153], off
	s_waitcnt vmcnt(8)
	s_waitcnt lgkmcnt(0)
	s_waitcnt lgkmcnt(0)
	v_mfma_f32_16x16x32_bf16 v[34:37], v[166:169], v[214:217], v[34:37]
	v_mfma_f32_16x16x32_bf16 v[46:49], v[178:181], v[214:217], v[46:49]
	s_barrier
	s_setprio 1
	v_mfma_f32_16x16x32_bf16 v[10:13], v[166:169], v[222:225], v[10:13]
	v_mfma_f32_16x16x32_bf16 v[6:9], v[178:181], v[222:225], v[6:9]
	v_mfma_f32_16x16x32_bf16 v[42:45], v[166:169], v[230:233], v[42:45]
	v_mfma_f32_16x16x32_bf16 v[58:61], v[178:181], v[230:233], v[58:61]
	v_mfma_f32_16x16x32_bf16 v[22:25], v[166:169], v[238:241], v[22:25]
	v_mfma_f32_16x16x32_bf16 v[2:5], v[178:181], v[238:241], v[2:5]
	v_mfma_f32_16x16x32_bf16 v[34:37], v[174:177], v[218:221], v[34:37]
	v_mfma_f32_16x16x32_bf16 v[46:49], v[182:185], v[218:221], v[46:49]
	v_mfma_f32_16x16x32_bf16 v[10:13], v[174:177], v[226:229], v[10:13]
	v_mfma_f32_16x16x32_bf16 v[6:9], v[182:185], v[226:229], v[6:9]
	v_mfma_f32_16x16x32_bf16 v[42:45], v[174:177], v[234:237], v[42:45]
	v_mfma_f32_16x16x32_bf16 v[58:61], v[182:185], v[234:237], v[58:61]
	v_mfma_f32_16x16x32_bf16 v[22:25], v[174:177], v[242:245], v[22:25]
	v_mfma_f32_16x16x32_bf16 v[2:5], v[182:185], v[242:245], v[2:5]
	s_setprio 0
	s_setprio 1
	v_mfma_f32_16x16x32_bf16 v[38:41], v[186:189], v[214:217], v[38:41]
	v_mfma_f32_16x16x32_bf16 v[54:57], v[206:209], v[214:217], v[54:57]
	v_mfma_f32_16x16x32_bf16 v[14:17], v[186:189], v[222:225], v[14:17]
	v_mfma_f32_16x16x32_bf16 v[26:29], v[206:209], v[222:225], v[26:29]
	v_mfma_f32_16x16x32_bf16 v[50:53], v[186:189], v[230:233], v[50:53]
	v_mfma_f32_16x16x32_bf16 v[62:65], v[206:209], v[230:233], v[62:65]
	v_mfma_f32_16x16x32_bf16 v[18:21], v[186:189], v[238:241], v[18:21]
	v_mfma_f32_16x16x32_bf16 v[30:33], v[206:209], v[238:241], v[30:33]
	v_mfma_f32_16x16x32_bf16 v[38:41], v[202:205], v[218:221], v[38:41]
	v_mfma_f32_16x16x32_bf16 v[54:57], v[210:213], v[218:221], v[54:57]
	v_mfma_f32_16x16x32_bf16 v[14:17], v[202:205], v[226:229], v[14:17]
	v_mfma_f32_16x16x32_bf16 v[26:29], v[210:213], v[226:229], v[26:29]
	v_mfma_f32_16x16x32_bf16 v[50:53], v[202:205], v[234:237], v[50:53]
	v_mfma_f32_16x16x32_bf16 v[62:65], v[210:213], v[234:237], v[62:65]
	v_mfma_f32_16x16x32_bf16 v[18:21], v[202:205], v[242:245], v[18:21]
	v_mfma_f32_16x16x32_bf16 v[30:33], v[210:213], v[242:245], v[30:33]
	s_setprio 0
	s_barrier
	s_add_i32 s50, s50, 2
	s_add_u32 s28, s28, 0x100
	s_addc_u32 s29, s29, 0
	s_cmp_gt_u32 s50, 29
	s_mov_b64 s[26:27], s[0:1]
	s_cbranch_scc0 .LBB0_375
	s_and_b64 vcc, exec, s[16:17]
	s_cbranch_vccz .LBB0_378
	s_barrier

; #define PG8_STAGE(bufoff, gbase, voff) do { _Pragma("unroll") for (int _i = 0; _i < 2; ++_i) \
;         __builtin_amdgcn_global_load_lds((const unsigned*)((const char*)(gbase) + (voff)[_i]), (PG8_LAS unsigned*)(lds + (bufoff) + ldsw + _i * 8192), 16, 0, 0); } while (0)
; #define PG8_LDA(dst, b, h) do { _Pragma("unroll") for (int m = 0; m < 4; ++m) _Pragma("unroll") for (int k = 0; k < 2; ++k) dst[m][k] = *(const PG8_LAS bf16x8*)(lds + PG8_SA(b, h) + aoff + m * 2048 + k * 1024); } while (0)
; #define PG8_LDB(dst, b, h) do { _Pragma("unroll") for (int n = 0; n < 2; ++n) _Pragma("unroll") for (int k = 0; k < 2; ++k) dst[n][k] = *(const PG8_LAS bf16x8*)(lds + PG8_SB(b, h) + boff + n * 2048 + k * 1024); } while (0)
; #define PG8_MMA(ai, bj, At, Bt) do { __builtin_amdgcn_s_setprio(1); _Pragma("unroll") for (int m = 0; m < 4; ++m) _Pragma("unroll") for (int n = 0; n < 2; ++n) _Pragma("unroll") for (int k = 0; k < 2; ++k) \
;         acc[ai][bj][m][n] = __builtin_amdgcn_mfma_f32_16x16x32_bf16(Bt[n][k], At[m][k], acc[ai][bj][m][n], 0, 0, 0); __builtin_amdgcn_s_setprio(0); } while (0)
; #define PG8_WAIT_V(n) asm volatile("s_waitcnt vmcnt(" #n ")" ::: "memory")
; #define PG8_WAIT_L(n) asm volatile("s_waitcnt lgkmcnt(" #n ")" ::: "memory")
; template <class Epi, class Sched, bool ALIGN_EPI = false, bool SP2 = false>
; __device__ __forceinline__ void gemm_phase(PG8_LAS unsigned char* lds, const Gemm g, const Sched& S, const Epi& E, const int wid_in) {
;     ...
;             const bool last = (t == nt - 2);
;             const char* a1 = cA + (size_t)(t + 1) * kstep;
;             const char* a2 = last ? nA : cA + (size_t)(t + 2) * kstep; const char* b2 = last ? nB : cB + (size_t)(t + 2) * kstep;
;             const char* a3 = a2 + kstep; const char* b3 = b2 + kstep;
;             if (last && has_next) S.a_ready(nxt);
;             if constexpr (SP2) {
;             PG8_LDB(B0, 0, 0); PG8_LDB(B1, 0, 1); PG8_SCHED; PG8_LDA(At, 0, 0); PG8_STAGE(PG8_SA(1, 1), a1 + hstepA, voffA);
;             PG8_WAIT_V(8); PG8_WAIT_L(0); PG8_BAR; PG8_MMA(0, 0, At, B0); PG8_MMA(0, 1, At, B1); PG8_BAR; PG8_SCHED;
;             PG8_LDA(At, 0, 1); PG8_STAGE(PG8_SB(0, 0), b2, voffB); PG8_STAGE(PG8_SB(0, 1), b2 + hstep, voffB); PG8_STAGE(PG8_SA(0, 0), a2, voffA);
;             PG8_WAIT_V(8); PG8_WAIT_L(0); PG8_BAR; PG8_MMA(1, 0, At, B0); PG8_MMA(1, 1, At, B1); PG8_BAR; PG8_SCHED;
.LBB0_484:
	s_add_u32 s0, s24, 0xfff80080
	s_addc_u32 s1, s25, -1
	s_add_i32 s49, 0, 0x10000
	s_cmp_eq_u32 s48, 28
	s_cselect_b32 s3, s19, s1
	s_cselect_b32 s2, s44, s0
	v_add_u32_e32 v150, s49, v152
	s_cselect_b32 s1, s17, s47
	s_cselect_b32 s0, s45, s46
	s_add_i32 s52, 0, 0x14000
	ds_read_b128 v[142:145], v150
	ds_read_b128 v[146:149], v150 offset:1024
	ds_read_b128 v[168:171], v150 offset:2048
	ds_read_b128 v[174:177], v150 offset:3072
	v_add_u32_e32 v150, s52, v152
	ds_read_b128 v[178:181], v150
	ds_read_b128 v[182:185], v150 offset:1024
	ds_read_b128 v[186:189], v150 offset:2048
	ds_read_b128 v[202:205], v150 offset:3072
	v_lshl_add_u64 v[150:151], s[24:25], 0, v[138:139]
	s_add_i32 m0, s35, 0xc000
	ds_read_b128 v[206:209], v167
	ds_read_b128 v[210:213], v167 offset:1024
	ds_read_b128 v[214:217], v167 offset:2048
	ds_read_b128 v[218:221], v167 offset:3072
	ds_read_b128 v[222:225], v167 offset:4096
	ds_read_b128 v[226:229], v167 offset:5120
	ds_read_b128 v[230:233], v167 offset:6144
	ds_read_b128 v[234:237], v167 offset:7168
	global_load_lds_dwordx4 v[150:151], off
	v_lshl_add_u64 v[150:151], s[24:25], 0, v[140:141]
	s_add_i32 m0, s35, 0xe000
	s_nop 0
	global_load_lds_dwordx4 v[150:151], off
	s_waitcnt vmcnt(8)
	s_waitcnt lgkmcnt(0)
	s_waitcnt lgkmcnt(0)
	v_mfma_f32_16x16x32_bf16 v[126:129], v[142:145], v[206:209], v[126:129]
	v_mfma_f32_16x16x32_bf16 v[122:125], v[168:171], v[206:209], v[122:125]
	s_barrier
	s_setprio 1
	v_mfma_f32_16x16x32_bf16 v[110:113], v[142:145], v[214:217], v[110:113]
	v_mfma_f32_16x16x32_bf16 v[106:109], v[168:171], v[214:217], v[106:109]
	v_mfma_f32_16x16x32_bf16 v[94:97], v[142:145], v[222:225], v[94:97]
	v_mfma_f32_16x16x32_bf16 v[90:93], v[168:171], v[222:225], v[90:93]
	v_mfma_f32_16x16x32_bf16 v[78:81], v[142:145], v[230:233], v[78:81]
	v_mfma_f32_16x16x32_bf16 v[74:77], v[168:171], v[230:233], v[74:77]
	v_mfma_f32_16x16x32_bf16 v[126:129], v[146:149], v[210:213], v[126:129]
	v_mfma_f32_16x16x32_bf16 v[122:125], v[174:177], v[210:213], v[122:125]
	v_mfma_f32_16x16x32_bf16 v[110:113], v[146:149], v[218:221], v[110:113]
	v_mfma_f32_16x16x32_bf16 v[106:109], v[174:177], v[218:221], v[106:109]
	v_mfma_f32_16x16x32_bf16 v[94:97], v[146:149], v[226:229], v[94:97]
	v_mfma_f32_16x16x32_bf16 v[90:93], v[174:177], v[226:229], v[90:93]
	v_mfma_f32_16x16x32_bf16 v[78:81], v[146:149], v[234:237], v[78:81]
	v_mfma_f32_16x16x32_bf16 v[74:77], v[174:177], v[234:237], v[74:77]
	s_setprio 0
	s_setprio 1
	v_mfma_f32_16x16x32_bf16 v[118:121], v[178:181], v[206:209], v[118:121]
	v_mfma_f32_16x16x32_bf16 v[114:117], v[186:189], v[206:209], v[114:117]
	v_mfma_f32_16x16x32_bf16 v[102:105], v[178:181], v[214:217], v[102:105]
	v_mfma_f32_16x16x32_bf16 v[98:101], v[186:189], v[214:217], v[98:101]
	v_mfma_f32_16x16x32_bf16 v[86:89], v[178:181], v[222:225], v[86:89]
	v_mfma_f32_16x16x32_bf16 v[82:85], v[186:189], v[222:225], v[82:85]
	v_mfma_f32_16x16x32_bf16 v[70:73], v[178:181], v[230:233], v[70:73]
	v_mfma_f32_16x16x32_bf16 v[66:69], v[186:189], v[230:233], v[66:69]
	v_mfma_f32_16x16x32_bf16 v[118:121], v[182:185], v[210:213], v[118:121]
	v_mfma_f32_16x16x32_bf16 v[114:117], v[202:205], v[210:213], v[114:117]
	v_mfma_f32_16x16x32_bf16 v[102:105], v[182:185], v[218:221], v[102:105]
	v_mfma_f32_16x16x32_bf16 v[98:101], v[202:205], v[218:221], v[98:101]
	v_mfma_f32_16x16x32_bf16 v[86:89], v[182:185], v[226:229], v[86:89]
	v_mfma_f32_16x16x32_bf16 v[82:85], v[202:205], v[226:229], v[82:85]
	v_mfma_f32_16x16x32_bf16 v[70:73], v[182:185], v[234:237], v[70:73]
	v_mfma_f32_16x16x32_bf16 v[66:69], v[202:205], v[234:237], v[66:69]
	s_setprio 0
	s_barrier
	s_add_i32 s49, s49, s29
	v_lshl_add_u64 v[150:151], s[0:1], 0, v[134:135]
	s_mov_b32 m0, s49
	ds_read_b128 v[206:209], v167 offset:16384
	ds_read_b128 v[210:213], v167 offset:17408
	ds_read_b128 v[214:217], v167 offset:18432
	ds_read_b128 v[218:221], v167 offset:19456
	ds_read_b128 v[222:225], v167 offset:20480
	ds_read_b128 v[226:229], v167 offset:21504
	ds_read_b128 v[230:233], v167 offset:22528
	ds_read_b128 v[234:237], v167 offset:23552
	global_load_lds_dwordx4 v[150:151], off
	s_add_i32 m0, s49, 0x2000
	s_add_u32 s50, s0, 0x80000
	v_lshl_add_u64 v[190:191], s[0:1], 0, v[130:131]
	s_addc_u32 s51, s1, 0
	s_add_i32 s49, s52, s29
	global_load_lds_dwordx4 v[190:191], off
	v_lshl_add_u64 v[238:239], s[50:51], 0, v[134:135]
	s_mov_b32 m0, s49
	v_lshl_add_u64 v[240:241], s[2:3], 0, v[132:133]
	global_load_lds_dwordx4 v[238:239], off
	v_lshl_add_u64 v[238:239], s[50:51], 0, v[130:131]
	s_add_i32 m0, s49, 0x2000
	s_nop 0
	global_load_lds_dwordx4 v[238:239], off
	v_lshl_add_u64 v[238:239], s[2:3], 0, v[136:137]
	s_mov_b32 m0, s35
	s_nop 0
	global_load_lds_dwordx4 v[238:239], off
	s_mov_b32 m0, s36
	s_nop 0
	global_load_lds_dwordx4 v[240:241], off
	s_waitcnt vmcnt(8)
	s_waitcnt lgkmcnt(0)
	s_waitcnt lgkmcnt(0)
	v_mfma_f32_16x16x32_bf16 v[62:65], v[142:145], v[206:209], v[62:65]
	v_mfma_f32_16x16x32_bf16 v[58:61], v[168:171], v[206:209], v[58:61]
	s_barrier
; #define PG8_STAGE(bufoff, gbase, voff) do { _Pragma("unroll") for (int _i = 0; _i < 2; ++_i) \
;         __builtin_amdgcn_global_load_lds((const unsigned*)((const char*)(gbase) + (voff)[_i]), (PG8_LAS unsigned*)(lds + (bufoff) + ldsw + _i * 8192), 16, 0, 0); } while (0)
; #define PG8_LDA(dst, b, h) do { _Pragma("unroll") for (int m = 0; m < 4; ++m) _Pragma("unroll") for (int k = 0; k < 2; ++k) dst[m][k] = *(const PG8_LAS bf16x8*)(lds + PG8_SA(b, h) + aoff + m * 2048 + k * 1024); } while (0)
; #define PG8_LDB(dst, b, h) do { _Pragma("unroll") for (int n = 0; n < 2; ++n) _Pragma("unroll") for (int k = 0; k < 2; ++k) dst[n][k] = *(const PG8_LAS bf16x8*)(lds + PG8_SB(b, h) + boff + n * 2048 + k * 1024); } while (0)
; #define PG8_MMA(ai, bj, At, Bt) do { __builtin_amdgcn_s_setprio(1); _Pragma("unroll") for (int m = 0; m < 4; ++m) _Pragma("unroll") for (int n = 0; n < 2; ++n) _Pragma("unroll") for (int k = 0; k < 2; ++k) \
;         acc[ai][bj][m][n] = __builtin_amdgcn_mfma_f32_16x16x32_bf16(Bt[n][k], At[m][k], acc[ai][bj][m][n], 0, 0, 0); __builtin_amdgcn_s_setprio(0); } while (0)
; #define PG8_WAIT_V(n) asm volatile("s_waitcnt vmcnt(" #n ")" ::: "memory")
; #define PG8_WAIT_L(n) asm volatile("s_waitcnt lgkmcnt(" #n ")" ::: "memory")
; #define PG8_BAR __builtin_amdgcn_s_barrier()
; #define PG8_SCHED __builtin_amdgcn_sched_barrier(0)
; template <class Epi, class Sched, bool ALIGN_EPI = false, bool SP2 = false>
; __device__ __forceinline__ void gemm_phase(PG8_LAS unsigned char* lds, const Gemm g, const Sched& S, const Epi& E, const int wid_in) {
;     ...
;             PG8_WAIT_V(8); PG8_WAIT_L(0); PG8_BAR; PG8_MMA(1, 0, At, B0); PG8_MMA(1, 1, At, B1); PG8_BAR; PG8_SCHED;
;             PG8_LDB(B0, 1, 0); PG8_LDB(B1, 1, 1); PG8_SCHED; PG8_LDA(At, 1, 0); PG8_STAGE(PG8_SA(0, 1), a2 + hstepA, voffA);
;             PG8_WAIT_V(8); PG8_WAIT_L(0); PG8_BAR; PG8_MMA(0, 0, At, B0); PG8_MMA(0, 1, At, B1); PG8_BAR; PG8_SCHED;
;             PG8_LDA(At, 1, 1); PG8_STAGE(PG8_SB(1, 0), b3, voffB); PG8_STAGE(PG8_SB(1, 1), b3 + hstep, voffB); PG8_STAGE(PG8_SA(1, 0), a3, voffA);
;             PG8_WAIT_V(8); PG8_WAIT_L(0); PG8_BAR; PG8_MMA(1, 0, At, B0); PG8_MMA(1, 1, At, B1); PG8_BAR; PG8_SCHED;
	s_setprio 1
	v_mfma_f32_16x16x32_bf16 v[46:49], v[142:145], v[214:217], v[46:49]
	v_mfma_f32_16x16x32_bf16 v[42:45], v[168:171], v[214:217], v[42:45]
	v_mfma_f32_16x16x32_bf16 v[30:33], v[142:145], v[222:225], v[30:33]
	v_mfma_f32_16x16x32_bf16 v[26:29], v[168:171], v[222:225], v[26:29]
	v_mfma_f32_16x16x32_bf16 v[14:17], v[142:145], v[230:233], v[14:17]
	v_mfma_f32_16x16x32_bf16 v[10:13], v[168:171], v[230:233], v[10:13]
	v_mfma_f32_16x16x32_bf16 v[62:65], v[146:149], v[210:213], v[62:65]
	v_mfma_f32_16x16x32_bf16 v[58:61], v[174:177], v[210:213], v[58:61]
	v_mfma_f32_16x16x32_bf16 v[46:49], v[146:149], v[218:221], v[46:49]
	v_mfma_f32_16x16x32_bf16 v[42:45], v[174:177], v[218:221], v[42:45]
	v_mfma_f32_16x16x32_bf16 v[30:33], v[146:149], v[226:229], v[30:33]
	v_mfma_f32_16x16x32_bf16 v[26:29], v[174:177], v[226:229], v[26:29]
	v_mfma_f32_16x16x32_bf16 v[14:17], v[146:149], v[234:237], v[14:17]
	v_mfma_f32_16x16x32_bf16 v[10:13], v[174:177], v[234:237], v[10:13]
	s_setprio 0
	s_setprio 1
	v_mfma_f32_16x16x32_bf16 v[54:57], v[178:181], v[206:209], v[54:57]
	v_mfma_f32_16x16x32_bf16 v[50:53], v[186:189], v[206:209], v[50:53]
	v_mfma_f32_16x16x32_bf16 v[38:41], v[178:181], v[214:217], v[38:41]
	v_mfma_f32_16x16x32_bf16 v[34:37], v[186:189], v[214:217], v[34:37]
	v_mfma_f32_16x16x32_bf16 v[22:25], v[178:181], v[222:225], v[22:25]
	v_mfma_f32_16x16x32_bf16 v[18:21], v[186:189], v[222:225], v[18:21]
	v_mfma_f32_16x16x32_bf16 v[6:9], v[178:181], v[230:233], v[6:9]
	v_mfma_f32_16x16x32_bf16 v[2:5], v[186:189], v[230:233], v[2:5]
	v_mfma_f32_16x16x32_bf16 v[54:57], v[182:185], v[210:213], v[54:57]
	v_mfma_f32_16x16x32_bf16 v[50:53], v[202:205], v[210:213], v[50:53]
	v_mfma_f32_16x16x32_bf16 v[38:41], v[182:185], v[218:221], v[38:41]
	v_mfma_f32_16x16x32_bf16 v[34:37], v[202:205], v[218:221], v[34:37]
	v_mfma_f32_16x16x32_bf16 v[22:25], v[182:185], v[226:229], v[22:25]
	v_mfma_f32_16x16x32_bf16 v[18:21], v[202:205], v[226:229], v[18:21]
	v_mfma_f32_16x16x32_bf16 v[6:9], v[182:185], v[234:237], v[6:9]
	v_mfma_f32_16x16x32_bf16 v[2:5], v[202:205], v[234:237], v[2:5]
	s_setprio 0
	s_barrier
	s_add_i32 s49, 0, 0x18000
	s_add_i32 s50, 0, 0x1c000
	v_add_u32_e32 v174, s49, v152
	v_add_u32_e32 v202, s50, v152
	ds_read_b128 v[142:145], v174
	ds_read_b128 v[146:149], v174 offset:1024
	ds_read_b128 v[168:171], v174 offset:2048
	ds_read_b128 v[174:177], v174 offset:3072
	ds_read_b128 v[178:181], v202
	ds_read_b128 v[182:185], v202 offset:1024
	ds_read_b128 v[186:189], v202 offset:2048
	ds_read_b128 v[202:205], v202 offset:3072
	s_add_u32 s2, s2, 0x80000
	s_addc_u32 s3, s3, 0
	s_mov_b32 m0, s37
	v_lshl_add_u64 v[242:243], s[2:3], 0, v[136:137]
	ds_read_b128 v[206:209], v167 offset:32768
	ds_read_b128 v[210:213], v167 offset:33792
	ds_read_b128 v[214:217], v167 offset:34816
	ds_read_b128 v[218:221], v167 offset:35840
	ds_read_b128 v[222:225], v167 offset:36864
	ds_read_b128 v[226:229], v167 offset:37888
	ds_read_b128 v[230:233], v167 offset:38912
	ds_read_b128 v[234:237], v167 offset:39936
	global_load_lds_dwordx4 v[242:243], off
	v_lshl_add_u64 v[242:243], s[2:3], 0, v[132:133]
	s_mov_b32 m0, s38
	s_nop 0
	global_load_lds_dwordx4 v[242:243], off
	s_waitcnt vmcnt(8)
	s_waitcnt lgkmcnt(0)
	s_waitcnt lgkmcnt(0)
	v_mfma_f32_16x16x32_bf16 v[126:129], v[142:145], v[206:209], v[126:129]
	v_mfma_f32_16x16x32_bf16 v[122:125], v[168:171], v[206:209], v[122:125]
	s_barrier
	s_setprio 1
	v_mfma_f32_16x16x32_bf16 v[110:113], v[142:145], v[214:217], v[110:113]
	v_mfma_f32_16x16x32_bf16 v[106:109], v[168:171], v[214:217], v[106:109]
	v_mfma_f32_16x16x32_bf16 v[94:97], v[142:145], v[222:225], v[94:97]
	v_mfma_f32_16x16x32_bf16 v[90:93], v[168:171], v[222:225], v[90:93]
	v_mfma_f32_16x16x32_bf16 v[78:81], v[142:145], v[230:233], v[78:81]
	v_mfma_f32_16x16x32_bf16 v[74:77], v[168:171], v[230:233], v[74:77]
	v_mfma_f32_16x16x32_bf16 v[126:129], v[146:149], v[210:213], v[126:129]
	v_mfma_f32_16x16x32_bf16 v[122:125], v[174:177], v[210:213], v[122:125]
	v_mfma_f32_16x16x32_bf16 v[110:113], v[146:149], v[218:221], v[110:113]
	v_mfma_f32_16x16x32_bf16 v[106:109], v[174:177], v[218:221], v[106:109]
	v_mfma_f32_16x16x32_bf16 v[94:97], v[146:149], v[226:229], v[94:97]
	v_mfma_f32_16x16x32_bf16 v[90:93], v[174:177], v[226:229], v[90:93]
	v_mfma_f32_16x16x32_bf16 v[78:81], v[146:149], v[234:237], v[78:81]
	v_mfma_f32_16x16x32_bf16 v[74:77], v[174:177], v[234:237], v[74:77]
	s_setprio 0
	s_setprio 1
	v_mfma_f32_16x16x32_bf16 v[118:121], v[178:181], v[206:209], v[118:121]
	v_mfma_f32_16x16x32_bf16 v[114:117], v[186:189], v[206:209], v[114:117]
	v_mfma_f32_16x16x32_bf16 v[102:105], v[178:181], v[214:217], v[102:105]
	v_mfma_f32_16x16x32_bf16 v[98:101], v[186:189], v[214:217], v[98:101]
	v_mfma_f32_16x16x32_bf16 v[86:89], v[178:181], v[222:225], v[86:89]
	v_mfma_f32_16x16x32_bf16 v[82:85], v[186:189], v[222:225], v[82:85]
	v_mfma_f32_16x16x32_bf16 v[70:73], v[178:181], v[230:233], v[70:73]
	v_mfma_f32_16x16x32_bf16 v[66:69], v[186:189], v[230:233], v[66:69]
	v_mfma_f32_16x16x32_bf16 v[118:121], v[182:185], v[210:213], v[118:121]
	v_mfma_f32_16x16x32_bf16 v[114:117], v[202:205], v[210:213], v[114:117]
	v_mfma_f32_16x16x32_bf16 v[102:105], v[182:185], v[218:221], v[102:105]
	v_mfma_f32_16x16x32_bf16 v[98:101], v[202:205], v[218:221], v[98:101]
	v_mfma_f32_16x16x32_bf16 v[86:89], v[182:185], v[226:229], v[86:89]
	v_mfma_f32_16x16x32_bf16 v[82:85], v[202:205], v[226:229], v[82:85]
	v_mfma_f32_16x16x32_bf16 v[70:73], v[182:185], v[234:237], v[70:73]
	v_mfma_f32_16x16x32_bf16 v[66:69], v[202:205], v[234:237], v[66:69]
	s_setprio 0
	s_barrier
; #define PG8_STAGE(bufoff, gbase, voff) do { _Pragma("unroll") for (int _i = 0; _i < 2; ++_i) \
;         __builtin_amdgcn_global_load_lds((const unsigned*)((const char*)(gbase) + (voff)[_i]), (PG8_LAS unsigned*)(lds + (bufoff) + ldsw + _i * 8192), 16, 0, 0); } while (0)
; #define PG8_LDA(dst, b, h) do { _Pragma("unroll") for (int m = 0; m < 4; ++m) _Pragma("unroll") for (int k = 0; k < 2; ++k) dst[m][k] = *(const PG8_LAS bf16x8*)(lds + PG8_SA(b, h) + aoff + m * 2048 + k * 1024); } while (0)
; #define PG8_MMA(ai, bj, At, Bt) do { __builtin_amdgcn_s_setprio(1); _Pragma("unroll") for (int m = 0; m < 4; ++m) _Pragma("unroll") for (int n = 0; n < 2; ++n) _Pragma("unroll") for (int k = 0; k < 2; ++k) \
;         acc[ai][bj][m][n] = __builtin_amdgcn_mfma_f32_16x16x32_bf16(Bt[n][k], At[m][k], acc[ai][bj][m][n], 0, 0, 0); __builtin_amdgcn_s_setprio(0); } while (0)
; #define PG8_WAIT_V(n) asm volatile("s_waitcnt vmcnt(" #n ")" ::: "memory")
; #define PG8_WAIT_L(n) asm volatile("s_waitcnt lgkmcnt(" #n ")" ::: "memory")
; #define PG8_BAR __builtin_amdgcn_s_barrier()
; #define PG8_SCHED __builtin_amdgcn_sched_barrier(0)
; template <class Epi, class Sched, bool ALIGN_EPI = false, bool SP2 = false>
; __device__ __forceinline__ void gemm_phase(PG8_LAS unsigned char* lds, const Gemm g, const Sched& S, const Epi& E, const int wid_in) {
;     ...
;         for (int t = 0; t < nt; t += 2) {
;             const bool last = (t == nt - 2);
;             const char* a1 = cA + (size_t)(t + 1) * kstep;
;             const char* a2 = last ? nA : cA + (size_t)(t + 2) * kstep; const char* b2 = last ? nB : cB + (size_t)(t + 2) * kstep;
;             const char* a3 = a2 + kstep; const char* b3 = b2 + kstep;
;     ...
;             PG8_LDA(At, 1, 1); PG8_STAGE(PG8_SB(1, 0), b3, voffB); PG8_STAGE(PG8_SB(1, 1), b3 + hstep, voffB); PG8_STAGE(PG8_SA(1, 0), a3, voffA);
;             PG8_WAIT_V(8); PG8_WAIT_L(0); PG8_BAR; PG8_MMA(1, 0, At, B0); PG8_MMA(1, 1, At, B1); PG8_BAR; PG8_SCHED;
	s_add_i32 s2, s49, s29
	v_lshl_add_u64 v[150:151], v[150:151], 0, s[98:99]
	s_mov_b32 m0, s2
	ds_read_b128 v[206:209], v167 offset:49152
	ds_read_b128 v[210:213], v167 offset:50176
	ds_read_b128 v[214:217], v167 offset:51200
	ds_read_b128 v[218:221], v167 offset:52224
	ds_read_b128 v[222:225], v167 offset:53248
	ds_read_b128 v[226:229], v167 offset:54272
	ds_read_b128 v[230:233], v167 offset:55296
	ds_read_b128 v[234:237], v167 offset:56320
	global_load_lds_dwordx4 v[150:151], off
	s_add_i32 m0, s2, 0x2000
	s_add_u32 s0, s0, 0x80080
	v_lshl_add_u64 v[150:151], v[190:191], 0, s[98:99]
	s_addc_u32 s1, s1, 0
	s_add_i32 s2, s50, s29
	global_load_lds_dwordx4 v[150:151], off
	v_lshl_add_u64 v[150:151], s[0:1], 0, v[134:135]
	s_mov_b32 m0, s2
	s_nop 0
	global_load_lds_dwordx4 v[150:151], off
	v_lshl_add_u64 v[150:151], s[0:1], 0, v[130:131]
	s_add_i32 m0, s2, 0x2000
	s_nop 0
	global_load_lds_dwordx4 v[150:151], off
	v_lshl_add_u64 v[150:151], v[238:239], 0, s[98:99]
	s_mov_b32 m0, s39
	s_nop 0
	global_load_lds_dwordx4 v[150:151], off
	v_lshl_add_u64 v[150:151], v[240:241], 0, s[98:99]
	s_mov_b32 m0, s40
	s_nop 0
	global_load_lds_dwordx4 v[150:151], off
	s_waitcnt vmcnt(8)
	s_waitcnt lgkmcnt(0)
	s_waitcnt lgkmcnt(0)
	v_mfma_f32_16x16x32_bf16 v[62:65], v[142:145], v[206:209], v[62:65]
	v_mfma_f32_16x16x32_bf16 v[58:61], v[168:171], v[206:209], v[58:61]
	s_barrier
	s_setprio 1
	v_mfma_f32_16x16x32_bf16 v[46:49], v[142:145], v[214:217], v[46:49]
	v_mfma_f32_16x16x32_bf16 v[42:45], v[168:171], v[214:217], v[42:45]
	v_mfma_f32_16x16x32_bf16 v[30:33], v[142:145], v[222:225], v[30:33]
	v_mfma_f32_16x16x32_bf16 v[26:29], v[168:171], v[222:225], v[26:29]
	v_mfma_f32_16x16x32_bf16 v[14:17], v[142:145], v[230:233], v[14:17]
	v_mfma_f32_16x16x32_bf16 v[10:13], v[168:171], v[230:233], v[10:13]
	v_mfma_f32_16x16x32_bf16 v[62:65], v[146:149], v[210:213], v[62:65]
	v_mfma_f32_16x16x32_bf16 v[58:61], v[174:177], v[210:213], v[58:61]
	v_mfma_f32_16x16x32_bf16 v[46:49], v[146:149], v[218:221], v[46:49]
	v_mfma_f32_16x16x32_bf16 v[42:45], v[174:177], v[218:221], v[42:45]
	v_mfma_f32_16x16x32_bf16 v[30:33], v[146:149], v[226:229], v[30:33]
	v_mfma_f32_16x16x32_bf16 v[26:29], v[174:177], v[226:229], v[26:29]
	v_mfma_f32_16x16x32_bf16 v[14:17], v[146:149], v[234:237], v[14:17]
	v_mfma_f32_16x16x32_bf16 v[10:13], v[174:177], v[234:237], v[10:13]
	s_setprio 0
	s_setprio 1
	v_mfma_f32_16x16x32_bf16 v[54:57], v[178:181], v[206:209], v[54:57]
	v_mfma_f32_16x16x32_bf16 v[50:53], v[186:189], v[206:209], v[50:53]
	v_mfma_f32_16x16x32_bf16 v[38:41], v[178:181], v[214:217], v[38:41]
	v_mfma_f32_16x16x32_bf16 v[34:37], v[186:189], v[214:217], v[34:37]
	v_mfma_f32_16x16x32_bf16 v[22:25], v[178:181], v[222:225], v[22:25]
	v_mfma_f32_16x16x32_bf16 v[18:21], v[186:189], v[222:225], v[18:21]
	v_mfma_f32_16x16x32_bf16 v[6:9], v[178:181], v[230:233], v[6:9]
	v_mfma_f32_16x16x32_bf16 v[2:5], v[186:189], v[230:233], v[2:5]
	v_mfma_f32_16x16x32_bf16 v[54:57], v[182:185], v[210:213], v[54:57]
	v_mfma_f32_16x16x32_bf16 v[50:53], v[202:205], v[210:213], v[50:53]
	v_mfma_f32_16x16x32_bf16 v[38:41], v[182:185], v[218:221], v[38:41]
	v_mfma_f32_16x16x32_bf16 v[34:37], v[202:205], v[218:221], v[34:37]
	v_mfma_f32_16x16x32_bf16 v[22:25], v[182:185], v[226:229], v[22:25]
	v_mfma_f32_16x16x32_bf16 v[18:21], v[202:205], v[226:229], v[18:21]
	v_mfma_f32_16x16x32_bf16 v[6:9], v[182:185], v[234:237], v[6:9]
	v_mfma_f32_16x16x32_bf16 v[2:5], v[202:205], v[234:237], v[2:5]
	s_setprio 0
	s_barrier
	s_add_i32 s48, s48, 2
	s_add_u32 s24, s24, 0x100
	s_addc_u32 s25, s25, 0
	s_add_u32 s46, s46, 0x100
	s_addc_u32 s47, s47, 0
	s_cmp_gt_u32 s48, 29
	s_cbranch_scc0 .LBB0_484
	s_and_b64 vcc, exec, s[14:15]
	s_cbranch_vccz .LBB0_487
	s_barrier

; #define PG8_STAGE(bufoff, gbase, voff) do { _Pragma("unroll") for (int _i = 0; _i < 2; ++_i) \
;         __builtin_amdgcn_global_load_lds((const unsigned*)((const char*)(gbase) + (voff)[_i]), (PG8_LAS unsigned*)(lds + (bufoff) + ldsw + _i * 8192), 16, 0, 0); } while (0)
; #define PG8_LDA(dst, b, h) do { _Pragma("unroll") for (int m = 0; m < 4; ++m) _Pragma("unroll") for (int k = 0; k < 2; ++k) dst[m][k] = *(const PG8_LAS bf16x8*)(lds + PG8_SA(b, h) + aoff + m * 2048 + k * 1024); } while (0)
; #define PG8_LDB(dst, b, h) do { _Pragma("unroll") for (int n = 0; n < 2; ++n) _Pragma("unroll") for (int k = 0; k < 2; ++k) dst[n][k] = *(const PG8_LAS bf16x8*)(lds + PG8_SB(b, h) + boff + n * 2048 + k * 1024); } while (0)
; #define PG8_MMA(ai, bj, At, Bt) do { __builtin_amdgcn_s_setprio(1); _Pragma("unroll") for (int m = 0; m < 4; ++m) _Pragma("unroll") for (int n = 0; n < 2; ++n) _Pragma("unroll") for (int k = 0; k < 2; ++k) \
;         acc[ai][bj][m][n] = __builtin_amdgcn_mfma_f32_16x16x32_bf16(Bt[n][k], At[m][k], acc[ai][bj][m][n], 0, 0, 0); __builtin_amdgcn_s_setprio(0); } while (0)
; #define PG8_WAIT_V(n) asm volatile("s_waitcnt vmcnt(" #n ")" ::: "memory")
; #define PG8_WAIT_L(n) asm volatile("s_waitcnt lgkmcnt(" #n ")" ::: "memory")
; template <class Epi, class Sched, bool ALIGN_EPI = false, bool SP2 = false>
; __device__ __forceinline__ void gemm_phase(PG8_LAS unsigned char* lds, const Gemm g, const Sched& S, const Epi& E, const int wid_in) {
;     ...
;             const bool last = (t == nt - 2);
;             const char* a1 = cA + (size_t)(t + 1) * kstep;
;             const char* a2 = last ? nA : cA + (size_t)(t + 2) * kstep; const char* b2 = last ? nB : cB + (size_t)(t + 2) * kstep;
;             const char* a3 = a2 + kstep; const char* b3 = b2 + kstep;
;             if (last && has_next) S.a_ready(nxt);
;             if constexpr (SP2) {
;             PG8_LDB(B0, 0, 0); PG8_LDB(B1, 0, 1); PG8_SCHED; PG8_LDA(At, 0, 0); PG8_STAGE(PG8_SA(1, 1), a1 + hstepA, voffA);
;             PG8_WAIT_V(8); PG8_WAIT_L(0); PG8_BAR; PG8_MMA(0, 0, At, B0); PG8_MMA(0, 1, At, B1); PG8_BAR; PG8_SCHED;
;             PG8_LDA(At, 0, 1); PG8_STAGE(PG8_SB(0, 0), b2, voffB); PG8_STAGE(PG8_SB(0, 1), b2 + hstep, voffB); PG8_STAGE(PG8_SA(0, 0), a2, voffA);
;             PG8_WAIT_V(8); PG8_WAIT_L(0); PG8_BAR; PG8_MMA(1, 0, At, B0); PG8_MMA(1, 1, At, B1); PG8_BAR; PG8_SCHED;
.LBB0_545:
	s_add_u32 s2, s0, 0xffe00080
	s_addc_u32 s3, s1, -1
	s_add_i32 s49, 0, 0x10000
	s_cmpk_eq_i32 s48, 0x7c
	s_cselect_b32 s9, s21, s3
	s_cselect_b32 s8, s46, s2
	v_add_u32_e32 v145, s49, v147
	s_cselect_b32 s3, s19, s27
	s_cselect_b32 s2, s47, s26
	s_add_i32 s52, 0, 0x14000
	ds_read_b128 v[166:169], v145
	ds_read_b128 v[174:177], v145 offset:1024
	ds_read_b128 v[178:181], v145 offset:2048
	ds_read_b128 v[182:185], v145 offset:3072
	v_add_u32_e32 v145, s52, v147
	ds_read_b128 v[186:189], v145
	ds_read_b128 v[202:205], v145 offset:1024
	ds_read_b128 v[206:209], v145 offset:2048
	ds_read_b128 v[210:213], v145 offset:3072
	v_lshl_add_u64 v[152:153], s[0:1], 0, v[140:141]
	s_add_i32 m0, s36, 0xc000
	ds_read_b128 v[214:217], v150
	ds_read_b128 v[218:221], v150 offset:1024
	ds_read_b128 v[222:225], v150 offset:2048
	ds_read_b128 v[226:229], v150 offset:3072
	ds_read_b128 v[230:233], v150 offset:4096
	ds_read_b128 v[234:237], v150 offset:5120
	ds_read_b128 v[238:241], v150 offset:6144
	ds_read_b128 v[242:245], v150 offset:7168
	global_load_lds_dwordx4 v[152:153], off
	v_lshl_add_u64 v[152:153], s[0:1], 0, v[142:143]
	s_add_i32 m0, s36, 0xe000
	s_nop 0
	global_load_lds_dwordx4 v[152:153], off
	s_waitcnt vmcnt(8)
	s_waitcnt lgkmcnt(0)
	s_waitcnt lgkmcnt(0)
	v_mfma_f32_16x16x32_bf16 v[118:121], v[166:169], v[214:217], v[118:121]
	v_mfma_f32_16x16x32_bf16 v[114:117], v[178:181], v[214:217], v[114:117]
	s_barrier
	s_setprio 1
	v_mfma_f32_16x16x32_bf16 v[98:101], v[166:169], v[222:225], v[98:101]
	v_mfma_f32_16x16x32_bf16 v[106:109], v[178:181], v[222:225], v[106:109]
	v_mfma_f32_16x16x32_bf16 v[82:85], v[166:169], v[230:233], v[82:85]
	v_mfma_f32_16x16x32_bf16 v[90:93], v[178:181], v[230:233], v[90:93]
	v_mfma_f32_16x16x32_bf16 v[74:77], v[166:169], v[238:241], v[74:77]
	v_mfma_f32_16x16x32_bf16 v[66:69], v[178:181], v[238:241], v[66:69]
	v_mfma_f32_16x16x32_bf16 v[118:121], v[174:177], v[218:221], v[118:121]
	v_mfma_f32_16x16x32_bf16 v[114:117], v[182:185], v[218:221], v[114:117]
	v_mfma_f32_16x16x32_bf16 v[98:101], v[174:177], v[226:229], v[98:101]
	v_mfma_f32_16x16x32_bf16 v[106:109], v[182:185], v[226:229], v[106:109]
	v_mfma_f32_16x16x32_bf16 v[82:85], v[174:177], v[234:237], v[82:85]
	v_mfma_f32_16x16x32_bf16 v[90:93], v[182:185], v[234:237], v[90:93]
	v_mfma_f32_16x16x32_bf16 v[74:77], v[174:177], v[242:245], v[74:77]
	v_mfma_f32_16x16x32_bf16 v[66:69], v[182:185], v[242:245], v[66:69]
	s_setprio 0
	s_setprio 1
	v_mfma_f32_16x16x32_bf16 v[122:125], v[186:189], v[214:217], v[122:125]
	v_mfma_f32_16x16x32_bf16 v[126:129], v[206:209], v[214:217], v[126:129]
	v_mfma_f32_16x16x32_bf16 v[102:105], v[186:189], v[222:225], v[102:105]
	v_mfma_f32_16x16x32_bf16 v[110:113], v[206:209], v[222:225], v[110:113]
	v_mfma_f32_16x16x32_bf16 v[86:89], v[186:189], v[230:233], v[86:89]
	v_mfma_f32_16x16x32_bf16 v[94:97], v[206:209], v[230:233], v[94:97]
	v_mfma_f32_16x16x32_bf16 v[70:73], v[186:189], v[238:241], v[70:73]
	v_mfma_f32_16x16x32_bf16 v[78:81], v[206:209], v[238:241], v[78:81]
	v_mfma_f32_16x16x32_bf16 v[122:125], v[202:205], v[218:221], v[122:125]
	v_mfma_f32_16x16x32_bf16 v[126:129], v[210:213], v[218:221], v[126:129]
	v_mfma_f32_16x16x32_bf16 v[102:105], v[202:205], v[226:229], v[102:105]
	v_mfma_f32_16x16x32_bf16 v[110:113], v[210:213], v[226:229], v[110:113]
	v_mfma_f32_16x16x32_bf16 v[86:89], v[202:205], v[234:237], v[86:89]
	v_mfma_f32_16x16x32_bf16 v[94:97], v[210:213], v[234:237], v[94:97]
	v_mfma_f32_16x16x32_bf16 v[70:73], v[202:205], v[242:245], v[70:73]
	v_mfma_f32_16x16x32_bf16 v[78:81], v[210:213], v[242:245], v[78:81]
	s_setprio 0
	s_barrier
	s_add_i32 s49, s49, s35
	v_lshl_add_u64 v[152:153], s[2:3], 0, v[134:135]
	s_mov_b32 m0, s49
	ds_read_b128 v[214:217], v150 offset:16384
	ds_read_b128 v[218:221], v150 offset:17408
	ds_read_b128 v[222:225], v150 offset:18432
	ds_read_b128 v[226:229], v150 offset:19456
	ds_read_b128 v[230:233], v150 offset:20480
	ds_read_b128 v[234:237], v150 offset:21504
	ds_read_b128 v[238:241], v150 offset:22528
	ds_read_b128 v[242:245], v150 offset:23552
	global_load_lds_dwordx4 v[152:153], off
	s_add_i32 m0, s49, 0x2000
	s_add_u32 s50, s2, 0x200000
	v_lshl_add_u64 v[170:171], s[2:3], 0, v[130:131]
	s_addc_u32 s51, s3, 0
	s_add_i32 s49, s52, s35
	global_load_lds_dwordx4 v[170:171], off
	v_lshl_add_u64 v[190:191], s[50:51], 0, v[134:135]
	s_mov_b32 m0, s49
	v_lshl_add_u64 v[246:247], s[8:9], 0, v[132:133]
	global_load_lds_dwordx4 v[190:191], off
	v_lshl_add_u64 v[190:191], s[50:51], 0, v[130:131]
	s_add_i32 m0, s49, 0x2000
	s_nop 0
	global_load_lds_dwordx4 v[190:191], off
	v_lshl_add_u64 v[190:191], s[8:9], 0, v[136:137]
	s_mov_b32 m0, s36
	s_nop 0
	global_load_lds_dwordx4 v[190:191], off
	s_mov_b32 m0, s37
	s_nop 0
	global_load_lds_dwordx4 v[246:247], off
	s_waitcnt vmcnt(8)
	s_waitcnt lgkmcnt(0)
	s_waitcnt lgkmcnt(0)
	v_mfma_f32_16x16x32_bf16 v[34:37], v[166:169], v[214:217], v[34:37]
	v_mfma_f32_16x16x32_bf16 v[46:49], v[178:181], v[214:217], v[46:49]
	s_barrier
; #define PG8_STAGE(bufoff, gbase, voff) do { _Pragma("unroll") for (int _i = 0; _i < 2; ++_i) \
;         __builtin_amdgcn_global_load_lds((const unsigned*)((const char*)(gbase) + (voff)[_i]), (PG8_LAS unsigned*)(lds + (bufoff) + ldsw + _i * 8192), 16, 0, 0); } while (0)
; #define PG8_LDA(dst, b, h) do { _Pragma("unroll") for (int m = 0; m < 4; ++m) _Pragma("unroll") for (int k = 0; k < 2; ++k) dst[m][k] = *(const PG8_LAS bf16x8*)(lds + PG8_SA(b, h) + aoff + m * 2048 + k * 1024); } while (0)
; #define PG8_LDB(dst, b, h) do { _Pragma("unroll") for (int n = 0; n < 2; ++n) _Pragma("unroll") for (int k = 0; k < 2; ++k) dst[n][k] = *(const PG8_LAS bf16x8*)(lds + PG8_SB(b, h) + boff + n * 2048 + k * 1024); } while (0)
; #define PG8_MMA(ai, bj, At, Bt) do { __builtin_amdgcn_s_setprio(1); _Pragma("unroll") for (int m = 0; m < 4; ++m) _Pragma("unroll") for (int n = 0; n < 2; ++n) _Pragma("unroll") for (int k = 0; k < 2; ++k) \
;         acc[ai][bj][m][n] = __builtin_amdgcn_mfma_f32_16x16x32_bf16(Bt[n][k], At[m][k], acc[ai][bj][m][n], 0, 0, 0); __builtin_amdgcn_s_setprio(0); } while (0)
; #define PG8_WAIT_V(n) asm volatile("s_waitcnt vmcnt(" #n ")" ::: "memory")
; #define PG8_WAIT_L(n) asm volatile("s_waitcnt lgkmcnt(" #n ")" ::: "memory")
; #define PG8_BAR __builtin_amdgcn_s_barrier()
; #define PG8_SCHED __builtin_amdgcn_sched_barrier(0)
; template <class Epi, class Sched, bool ALIGN_EPI = false, bool SP2 = false>
; __device__ __forceinline__ void gemm_phase(PG8_LAS unsigned char* lds, const Gemm g, const Sched& S, const Epi& E, const int wid_in) {
;     ...
;             PG8_WAIT_V(8); PG8_WAIT_L(0); PG8_BAR; PG8_MMA(1, 0, At, B0); PG8_MMA(1, 1, At, B1); PG8_BAR; PG8_SCHED;
;             PG8_LDB(B0, 1, 0); PG8_LDB(B1, 1, 1); PG8_SCHED; PG8_LDA(At, 1, 0); PG8_STAGE(PG8_SA(0, 1), a2 + hstepA, voffA);
;             PG8_WAIT_V(8); PG8_WAIT_L(0); PG8_BAR; PG8_MMA(0, 0, At, B0); PG8_MMA(0, 1, At, B1); PG8_BAR; PG8_SCHED;
;             PG8_LDA(At, 1, 1); PG8_STAGE(PG8_SB(1, 0), b3, voffB); PG8_STAGE(PG8_SB(1, 1), b3 + hstep, voffB); PG8_STAGE(PG8_SA(1, 0), a3, voffA);
;             PG8_WAIT_V(8); PG8_WAIT_L(0); PG8_BAR; PG8_MMA(1, 0, At, B0); PG8_MMA(1, 1, At, B1); PG8_BAR; PG8_SCHED;
	s_setprio 1
	v_mfma_f32_16x16x32_bf16 v[10:13], v[166:169], v[222:225], v[10:13]
	v_mfma_f32_16x16x32_bf16 v[6:9], v[178:181], v[222:225], v[6:9]
	v_mfma_f32_16x16x32_bf16 v[42:45], v[166:169], v[230:233], v[42:45]
	v_mfma_f32_16x16x32_bf16 v[58:61], v[178:181], v[230:233], v[58:61]
	v_mfma_f32_16x16x32_bf16 v[22:25], v[166:169], v[238:241], v[22:25]
	v_mfma_f32_16x16x32_bf16 v[2:5], v[178:181], v[238:241], v[2:5]
	v_mfma_f32_16x16x32_bf16 v[34:37], v[174:177], v[218:221], v[34:37]
	v_mfma_f32_16x16x32_bf16 v[46:49], v[182:185], v[218:221], v[46:49]
	v_mfma_f32_16x16x32_bf16 v[10:13], v[174:177], v[226:229], v[10:13]
	v_mfma_f32_16x16x32_bf16 v[6:9], v[182:185], v[226:229], v[6:9]
	v_mfma_f32_16x16x32_bf16 v[42:45], v[174:177], v[234:237], v[42:45]
	v_mfma_f32_16x16x32_bf16 v[58:61], v[182:185], v[234:237], v[58:61]
	v_mfma_f32_16x16x32_bf16 v[22:25], v[174:177], v[242:245], v[22:25]
	v_mfma_f32_16x16x32_bf16 v[2:5], v[182:185], v[242:245], v[2:5]
	s_setprio 0
	s_setprio 1
	v_mfma_f32_16x16x32_bf16 v[38:41], v[186:189], v[214:217], v[38:41]
	v_mfma_f32_16x16x32_bf16 v[54:57], v[206:209], v[214:217], v[54:57]
	v_mfma_f32_16x16x32_bf16 v[14:17], v[186:189], v[222:225], v[14:17]
	v_mfma_f32_16x16x32_bf16 v[26:29], v[206:209], v[222:225], v[26:29]
	v_mfma_f32_16x16x32_bf16 v[50:53], v[186:189], v[230:233], v[50:53]
	v_mfma_f32_16x16x32_bf16 v[62:65], v[206:209], v[230:233], v[62:65]
	v_mfma_f32_16x16x32_bf16 v[18:21], v[186:189], v[238:241], v[18:21]
	v_mfma_f32_16x16x32_bf16 v[30:33], v[206:209], v[238:241], v[30:33]
	v_mfma_f32_16x16x32_bf16 v[38:41], v[202:205], v[218:221], v[38:41]
	v_mfma_f32_16x16x32_bf16 v[54:57], v[210:213], v[218:221], v[54:57]
	v_mfma_f32_16x16x32_bf16 v[14:17], v[202:205], v[226:229], v[14:17]
	v_mfma_f32_16x16x32_bf16 v[26:29], v[210:213], v[226:229], v[26:29]
	v_mfma_f32_16x16x32_bf16 v[50:53], v[202:205], v[234:237], v[50:53]
	v_mfma_f32_16x16x32_bf16 v[62:65], v[210:213], v[234:237], v[62:65]
	v_mfma_f32_16x16x32_bf16 v[18:21], v[202:205], v[242:245], v[18:21]
	v_mfma_f32_16x16x32_bf16 v[30:33], v[210:213], v[242:245], v[30:33]
	s_setprio 0
	s_barrier
	s_add_i32 s49, 0, 0x18000
	v_add_u32_e32 v145, s49, v147
	s_add_i32 s50, 0, 0x1c000
	ds_read_b128 v[166:169], v145
	ds_read_b128 v[174:177], v145 offset:1024
	ds_read_b128 v[178:181], v145 offset:2048
	ds_read_b128 v[182:185], v145 offset:3072
	v_add_u32_e32 v145, s50, v147
	ds_read_b128 v[186:189], v145
	ds_read_b128 v[202:205], v145 offset:1024
	ds_read_b128 v[206:209], v145 offset:2048
	ds_read_b128 v[210:213], v145 offset:3072
	s_add_u32 s8, s8, 0x200000
	s_addc_u32 s9, s9, 0
	s_mov_b32 m0, s38
	v_lshl_add_u64 v[248:249], s[8:9], 0, v[136:137]
	ds_read_b128 v[214:217], v150 offset:32768
	ds_read_b128 v[218:221], v150 offset:33792
	ds_read_b128 v[222:225], v150 offset:34816
	ds_read_b128 v[226:229], v150 offset:35840
	ds_read_b128 v[230:233], v150 offset:36864
	ds_read_b128 v[234:237], v150 offset:37888
	ds_read_b128 v[238:241], v150 offset:38912
	ds_read_b128 v[242:245], v150 offset:39936
	global_load_lds_dwordx4 v[248:249], off
	v_lshl_add_u64 v[248:249], s[8:9], 0, v[132:133]
	s_mov_b32 m0, s39
	s_nop 0
	global_load_lds_dwordx4 v[248:249], off
	s_waitcnt vmcnt(8)
	s_waitcnt lgkmcnt(0)
	s_waitcnt lgkmcnt(0)
	v_mfma_f32_16x16x32_bf16 v[118:121], v[166:169], v[214:217], v[118:121]
	v_mfma_f32_16x16x32_bf16 v[114:117], v[178:181], v[214:217], v[114:117]
	s_barrier
	s_setprio 1
	v_mfma_f32_16x16x32_bf16 v[98:101], v[166:169], v[222:225], v[98:101]
	v_mfma_f32_16x16x32_bf16 v[106:109], v[178:181], v[222:225], v[106:109]
	v_mfma_f32_16x16x32_bf16 v[82:85], v[166:169], v[230:233], v[82:85]
	v_mfma_f32_16x16x32_bf16 v[90:93], v[178:181], v[230:233], v[90:93]
	v_mfma_f32_16x16x32_bf16 v[74:77], v[166:169], v[238:241], v[74:77]
	v_mfma_f32_16x16x32_bf16 v[66:69], v[178:181], v[238:241], v[66:69]
	v_mfma_f32_16x16x32_bf16 v[118:121], v[174:177], v[218:221], v[118:121]
	v_mfma_f32_16x16x32_bf16 v[114:117], v[182:185], v[218:221], v[114:117]
	v_mfma_f32_16x16x32_bf16 v[98:101], v[174:177], v[226:229], v[98:101]
	v_mfma_f32_16x16x32_bf16 v[106:109], v[182:185], v[226:229], v[106:109]
	v_mfma_f32_16x16x32_bf16 v[82:85], v[174:177], v[234:237], v[82:85]
	v_mfma_f32_16x16x32_bf16 v[90:93], v[182:185], v[234:237], v[90:93]
	v_mfma_f32_16x16x32_bf16 v[74:77], v[174:177], v[242:245], v[74:77]
	v_mfma_f32_16x16x32_bf16 v[66:69], v[182:185], v[242:245], v[66:69]
	s_setprio 0
	s_setprio 1
	v_mfma_f32_16x16x32_bf16 v[122:125], v[186:189], v[214:217], v[122:125]
	v_mfma_f32_16x16x32_bf16 v[126:129], v[206:209], v[214:217], v[126:129]
	v_mfma_f32_16x16x32_bf16 v[102:105], v[186:189], v[222:225], v[102:105]
	v_mfma_f32_16x16x32_bf16 v[110:113], v[206:209], v[222:225], v[110:113]
	v_mfma_f32_16x16x32_bf16 v[86:89], v[186:189], v[230:233], v[86:89]
	v_mfma_f32_16x16x32_bf16 v[94:97], v[206:209], v[230:233], v[94:97]
	v_mfma_f32_16x16x32_bf16 v[70:73], v[186:189], v[238:241], v[70:73]
	v_mfma_f32_16x16x32_bf16 v[78:81], v[206:209], v[238:241], v[78:81]
	v_mfma_f32_16x16x32_bf16 v[122:125], v[202:205], v[218:221], v[122:125]
	v_mfma_f32_16x16x32_bf16 v[126:129], v[210:213], v[218:221], v[126:129]
	v_mfma_f32_16x16x32_bf16 v[102:105], v[202:205], v[226:229], v[102:105]
	v_mfma_f32_16x16x32_bf16 v[110:113], v[210:213], v[226:229], v[110:113]
	v_mfma_f32_16x16x32_bf16 v[86:89], v[202:205], v[234:237], v[86:89]
	v_mfma_f32_16x16x32_bf16 v[94:97], v[210:213], v[234:237], v[94:97]
	v_mfma_f32_16x16x32_bf16 v[70:73], v[202:205], v[242:245], v[70:73]
	v_mfma_f32_16x16x32_bf16 v[78:81], v[210:213], v[242:245], v[78:81]
	s_setprio 0
	s_barrier
; #define PG8_STAGE(bufoff, gbase, voff) do { _Pragma("unroll") for (int _i = 0; _i < 2; ++_i) \
;         __builtin_amdgcn_global_load_lds((const unsigned*)((const char*)(gbase) + (voff)[_i]), (PG8_LAS unsigned*)(lds + (bufoff) + ldsw + _i * 8192), 16, 0, 0); } while (0)
; #define PG8_LDA(dst, b, h) do { _Pragma("unroll") for (int m = 0; m < 4; ++m) _Pragma("unroll") for (int k = 0; k < 2; ++k) dst[m][k] = *(const PG8_LAS bf16x8*)(lds + PG8_SA(b, h) + aoff + m * 2048 + k * 1024); } while (0)
; #define PG8_MMA(ai, bj, At, Bt) do { __builtin_amdgcn_s_setprio(1); _Pragma("unroll") for (int m = 0; m < 4; ++m) _Pragma("unroll") for (int n = 0; n < 2; ++n) _Pragma("unroll") for (int k = 0; k < 2; ++k) \
;         acc[ai][bj][m][n] = __builtin_amdgcn_mfma_f32_16x16x32_bf16(Bt[n][k], At[m][k], acc[ai][bj][m][n], 0, 0, 0); __builtin_amdgcn_s_setprio(0); } while (0)
; #define PG8_WAIT_V(n) asm volatile("s_waitcnt vmcnt(" #n ")" ::: "memory")
; #define PG8_WAIT_L(n) asm volatile("s_waitcnt lgkmcnt(" #n ")" ::: "memory")
; #define PG8_BAR __builtin_amdgcn_s_barrier()
; #define PG8_SCHED __builtin_amdgcn_sched_barrier(0)
; template <class Epi, class Sched, bool ALIGN_EPI = false, bool SP2 = false>
; __device__ __forceinline__ void gemm_phase(PG8_LAS unsigned char* lds, const Gemm g, const Sched& S, const Epi& E, const int wid_in) {
;     ...
;         for (int t = 0; t < nt; t += 2) {
;             const bool last = (t == nt - 2);
;             const char* a1 = cA + (size_t)(t + 1) * kstep;
;             const char* a2 = last ? nA : cA + (size_t)(t + 2) * kstep; const char* b2 = last ? nB : cB + (size_t)(t + 2) * kstep;
;             const char* a3 = a2 + kstep; const char* b3 = b2 + kstep;
;     ...
;             PG8_LDA(At, 1, 1); PG8_STAGE(PG8_SB(1, 0), b3, voffB); PG8_STAGE(PG8_SB(1, 1), b3 + hstep, voffB); PG8_STAGE(PG8_SA(1, 0), a3, voffA);
;             PG8_WAIT_V(8); PG8_WAIT_L(0); PG8_BAR; PG8_MMA(1, 0, At, B0); PG8_MMA(1, 1, At, B1); PG8_BAR; PG8_SCHED;
	s_add_i32 s8, s49, s35
	v_lshl_add_u64 v[152:153], v[152:153], 0, s[98:99]
	s_mov_b32 m0, s8
	ds_read_b128 v[214:217], v150 offset:49152
	ds_read_b128 v[218:221], v150 offset:50176
	ds_read_b128 v[222:225], v150 offset:51200
	ds_read_b128 v[226:229], v150 offset:52224
	ds_read_b128 v[230:233], v150 offset:53248
	ds_read_b128 v[234:237], v150 offset:54272
	ds_read_b128 v[238:241], v150 offset:55296
	ds_read_b128 v[242:245], v150 offset:56320
	global_load_lds_dwordx4 v[152:153], off
	s_add_i32 m0, s8, 0x2000
	s_add_u32 s2, s2, 0x200080
	v_lshl_add_u64 v[152:153], v[170:171], 0, s[98:99]
	s_addc_u32 s3, s3, 0
	s_add_i32 s8, s50, s35
	global_load_lds_dwordx4 v[152:153], off
	v_lshl_add_u64 v[152:153], s[2:3], 0, v[134:135]
	s_mov_b32 m0, s8
	s_nop 0
	global_load_lds_dwordx4 v[152:153], off
	v_lshl_add_u64 v[152:153], s[2:3], 0, v[130:131]
	s_add_i32 m0, s8, 0x2000
	s_nop 0
	global_load_lds_dwordx4 v[152:153], off
	v_lshl_add_u64 v[152:153], v[190:191], 0, s[98:99]
	s_mov_b32 m0, s42
	s_nop 0
	global_load_lds_dwordx4 v[152:153], off
	v_lshl_add_u64 v[152:153], v[246:247], 0, s[98:99]
	s_mov_b32 m0, s43
	s_nop 0
	global_load_lds_dwordx4 v[152:153], off
	s_waitcnt vmcnt(8)
	s_waitcnt lgkmcnt(0)
	s_waitcnt lgkmcnt(0)
	v_mfma_f32_16x16x32_bf16 v[34:37], v[166:169], v[214:217], v[34:37]
	v_mfma_f32_16x16x32_bf16 v[46:49], v[178:181], v[214:217], v[46:49]
	s_barrier
	s_setprio 1
	v_mfma_f32_16x16x32_bf16 v[10:13], v[166:169], v[222:225], v[10:13]
	v_mfma_f32_16x16x32_bf16 v[6:9], v[178:181], v[222:225], v[6:9]
	v_mfma_f32_16x16x32_bf16 v[42:45], v[166:169], v[230:233], v[42:45]
	v_mfma_f32_16x16x32_bf16 v[58:61], v[178:181], v[230:233], v[58:61]
	v_mfma_f32_16x16x32_bf16 v[22:25], v[166:169], v[238:241], v[22:25]
	v_mfma_f32_16x16x32_bf16 v[2:5], v[178:181], v[238:241], v[2:5]
	v_mfma_f32_16x16x32_bf16 v[34:37], v[174:177], v[218:221], v[34:37]
	v_mfma_f32_16x16x32_bf16 v[46:49], v[182:185], v[218:221], v[46:49]
	v_mfma_f32_16x16x32_bf16 v[10:13], v[174:177], v[226:229], v[10:13]
	v_mfma_f32_16x16x32_bf16 v[6:9], v[182:185], v[226:229], v[6:9]
	v_mfma_f32_16x16x32_bf16 v[42:45], v[174:177], v[234:237], v[42:45]
	v_mfma_f32_16x16x32_bf16 v[58:61], v[182:185], v[234:237], v[58:61]
	v_mfma_f32_16x16x32_bf16 v[22:25], v[174:177], v[242:245], v[22:25]
	v_mfma_f32_16x16x32_bf16 v[2:5], v[182:185], v[242:245], v[2:5]
	s_setprio 0
	s_setprio 1
	v_mfma_f32_16x16x32_bf16 v[38:41], v[186:189], v[214:217], v[38:41]
	v_mfma_f32_16x16x32_bf16 v[54:57], v[206:209], v[214:217], v[54:57]
	v_mfma_f32_16x16x32_bf16 v[14:17], v[186:189], v[222:225], v[14:17]
	v_mfma_f32_16x16x32_bf16 v[26:29], v[206:209], v[222:225], v[26:29]
	v_mfma_f32_16x16x32_bf16 v[50:53], v[186:189], v[230:233], v[50:53]
	v_mfma_f32_16x16x32_bf16 v[62:65], v[206:209], v[230:233], v[62:65]
	v_mfma_f32_16x16x32_bf16 v[18:21], v[186:189], v[238:241], v[18:21]
	v_mfma_f32_16x16x32_bf16 v[30:33], v[206:209], v[238:241], v[30:33]
	v_mfma_f32_16x16x32_bf16 v[38:41], v[202:205], v[218:221], v[38:41]
	v_mfma_f32_16x16x32_bf16 v[54:57], v[210:213], v[218:221], v[54:57]
	v_mfma_f32_16x16x32_bf16 v[14:17], v[202:205], v[226:229], v[14:17]
	v_mfma_f32_16x16x32_bf16 v[26:29], v[210:213], v[226:229], v[26:29]
	v_mfma_f32_16x16x32_bf16 v[50:53], v[202:205], v[234:237], v[50:53]
	v_mfma_f32_16x16x32_bf16 v[62:65], v[210:213], v[234:237], v[62:65]
	v_mfma_f32_16x16x32_bf16 v[18:21], v[202:205], v[242:245], v[18:21]
	v_mfma_f32_16x16x32_bf16 v[30:33], v[210:213], v[242:245], v[30:33]
	s_setprio 0
	s_barrier
	s_add_i32 s48, s48, 2
	s_add_u32 s0, s0, 0x100
	s_addc_u32 s1, s1, 0
	s_add_u32 s26, s26, 0x100
	s_addc_u32 s27, s27, 0
	s_cmpk_gt_u32 s48, 0x7d
	s_cbranch_scc0 .LBB0_545
	s_and_b64 vcc, exec, s[14:15]
	s_cbranch_vccz .LBB0_548
	s_barrier
